# K-loops: the two remaining per-trip VALU adds (second tile's LDS read bases) hoisted out of the loop into the freed address registers
# baseline (speedup 1.0000x reference)
.LBB0_150:
	s_ashr_i32 s19, s18, 31
	s_lshl_b64 s[20:21], s[18:19], 20
	s_add_u32 s20, s34, s20
	s_addc_u32 s21, s35, s21
	s_and_b64 s[44:45], s[4:5], exec
	s_cselect_b32 s19, s21, s49
	s_cselect_b32 s72, s20, s48
	s_ashr_i32 s15, s14, 31
	s_lshl_b64 s[44:45], s[14:15], 20
	s_add_u32 s44, s16, s44
	s_addc_u32 s45, s17, s45
	s_and_b64 s[58:59], s[4:5], exec
	s_cselect_b32 s15, s45, s51
	s_cselect_b32 s73, s44, s50
	s_add_u32 s48, s48, 0x80080
	s_addc_u32 s49, s49, 0
	s_add_u32 s74, s50, 0x100
	v_mov_b32_e32 v0, 0
	s_addc_u32 s75, s51, 0
	s_mov_b32 s76, -2
	v_mov_b32_e32 v1, v0
	v_mov_b32_e32 v2, v0
	v_mov_b32_e32 v3, v0
	v_mov_b32_e32 v4, v0
	v_mov_b32_e32 v5, v0
	v_mov_b32_e32 v6, v0
	v_mov_b32_e32 v7, v0
	v_mov_b32_e32 v16, v0
	v_mov_b32_e32 v17, v0
	v_mov_b32_e32 v18, v0
	v_mov_b32_e32 v19, v0
	v_mov_b32_e32 v20, v0
	v_mov_b32_e32 v21, v0
	v_mov_b32_e32 v22, v0
	v_mov_b32_e32 v23, v0
	v_mov_b32_e32 v32, v0
	v_mov_b32_e32 v33, v0
	v_mov_b32_e32 v34, v0
	v_mov_b32_e32 v35, v0
	v_mov_b32_e32 v36, v0
	v_mov_b32_e32 v37, v0
	v_mov_b32_e32 v38, v0
	v_mov_b32_e32 v39, v0
	v_mov_b32_e32 v48, v0
	v_mov_b32_e32 v49, v0
	v_mov_b32_e32 v50, v0
	v_mov_b32_e32 v51, v0
	v_mov_b32_e32 v52, v0
	v_mov_b32_e32 v53, v0
	v_mov_b32_e32 v54, v0
	v_mov_b32_e32 v55, v0
	v_mov_b32_e32 v8, v0
	v_mov_b32_e32 v9, v0
	v_mov_b32_e32 v10, v0
	v_mov_b32_e32 v11, v0
	v_mov_b32_e32 v12, v0
	v_mov_b32_e32 v13, v0
	v_mov_b32_e32 v14, v0
	v_mov_b32_e32 v15, v0
	v_mov_b32_e32 v24, v0
	v_mov_b32_e32 v25, v0
	v_mov_b32_e32 v26, v0
	v_mov_b32_e32 v27, v0
	v_mov_b32_e32 v28, v0
	v_mov_b32_e32 v29, v0
	v_mov_b32_e32 v30, v0
	v_mov_b32_e32 v31, v0
	v_mov_b32_e32 v40, v0
	v_mov_b32_e32 v41, v0
	v_mov_b32_e32 v42, v0
	v_mov_b32_e32 v43, v0
	v_mov_b32_e32 v44, v0
	v_mov_b32_e32 v45, v0
	v_mov_b32_e32 v46, v0
	v_mov_b32_e32 v47, v0
	v_mov_b32_e32 v56, v0
	v_mov_b32_e32 v57, v0
	v_mov_b32_e32 v58, v0
	v_mov_b32_e32 v59, v0
	v_mov_b32_e32 v60, v0
	v_mov_b32_e32 v61, v0
	v_mov_b32_e32 v62, v0
	v_mov_b32_e32 v63, v0
	v_mov_b32_e32 v64, v0
	v_mov_b32_e32 v65, v0
	v_mov_b32_e32 v66, v0
	v_mov_b32_e32 v67, v0
	v_mov_b32_e32 v68, v0
	v_mov_b32_e32 v69, v0
	v_mov_b32_e32 v70, v0
	v_mov_b32_e32 v71, v0
	v_mov_b32_e32 v80, v0
	v_mov_b32_e32 v81, v0
	v_mov_b32_e32 v82, v0
	v_mov_b32_e32 v83, v0
	v_mov_b32_e32 v84, v0
	v_mov_b32_e32 v85, v0
	v_mov_b32_e32 v86, v0
	v_mov_b32_e32 v87, v0
	v_mov_b32_e32 v96, v0
	v_mov_b32_e32 v97, v0
	v_mov_b32_e32 v98, v0
	v_mov_b32_e32 v99, v0
	v_mov_b32_e32 v100, v0
	v_mov_b32_e32 v101, v0
	v_mov_b32_e32 v102, v0
	v_mov_b32_e32 v103, v0
	v_mov_b32_e32 v104, v0
	v_mov_b32_e32 v105, v0
	v_mov_b32_e32 v106, v0
	v_mov_b32_e32 v107, v0
	v_mov_b32_e32 v108, v0
	v_mov_b32_e32 v109, v0
	v_mov_b32_e32 v110, v0
	v_mov_b32_e32 v111, v0
	v_mov_b32_e32 v72, v0
	v_mov_b32_e32 v73, v0
	v_mov_b32_e32 v74, v0
	v_mov_b32_e32 v75, v0
	v_mov_b32_e32 v76, v0
	v_mov_b32_e32 v77, v0
	v_mov_b32_e32 v78, v0
	v_mov_b32_e32 v79, v0
	v_mov_b32_e32 v88, v0
	v_mov_b32_e32 v89, v0
	v_mov_b32_e32 v90, v0
	v_mov_b32_e32 v91, v0
	v_mov_b32_e32 v92, v0
	v_mov_b32_e32 v93, v0
	v_mov_b32_e32 v94, v0
	v_mov_b32_e32 v95, v0
	v_mov_b32_e32 v112, v0
	v_mov_b32_e32 v113, v0
	v_mov_b32_e32 v114, v0
	v_mov_b32_e32 v115, v0
	v_mov_b32_e32 v116, v0
	v_mov_b32_e32 v117, v0
	v_mov_b32_e32 v118, v0
	v_mov_b32_e32 v119, v0
	v_mov_b32_e32 v120, v0
	v_mov_b32_e32 v121, v0
	v_mov_b32_e32 v122, v0
	v_mov_b32_e32 v123, v0
	v_mov_b32_e32 v124, v0
	v_mov_b32_e32 v125, v0
	v_mov_b32_e32 v126, v0
	v_mov_b32_e32 v127, v0
	v_add_u32_e32 v148, 0x18000, v153
	v_add_u32_e32 v149, 0x1c000, v153
.LBB0_151:
	ds_read_b128 v[144:147], v157
	ds_read_b128 v[162:165], v157 offset:1024
	ds_read_b128 v[166:169], v157 offset:2048
	ds_read_b128 v[170:173], v157 offset:3072
	ds_read_b128 v[174:177], v159
	ds_read_b128 v[178:181], v159 offset:1024
	ds_read_b128 v[182:185], v159 offset:2048
	ds_read_b128 v[186:189], v159 offset:3072
	s_add_u32 s50, s48, 0xfff80080
	s_addc_u32 s51, s49, -1
	s_cmp_eq_u32 s76, 28
	s_cselect_b32 s59, s19, s51
	s_cselect_b32 s58, s72, s50
	s_cselect_b32 s51, s15, s75
	s_cselect_b32 s50, s73, s74
	s_add_i32 m0, s47, 0xc000
	ds_read_b128 v[190:193], v160
	ds_read_b128 v[194:197], v160 offset:1024
	ds_read_b128 v[198:201], v160 offset:2048
	ds_read_b128 v[202:205], v160 offset:3072
	ds_read_b128 v[206:209], v160 offset:4096
	ds_read_b128 v[210:213], v160 offset:5120
	ds_read_b128 v[214:217], v160 offset:6144
	ds_read_b128 v[218:221], v160 offset:7168
	global_load_lds_dwordx4 v136, s[48:49]
	s_add_i32 m0, s47, 0xe000
	s_nop 0
	global_load_lds_dwordx4 v138, s[48:49]
	s_waitcnt vmcnt(8)
	s_waitcnt lgkmcnt(0)
	s_barrier
	s_setprio 3
	s_waitcnt lgkmcnt(0)
	v_mfma_f32_16x16x32_bf16 v[124:127], v[144:147], v[190:193], v[124:127]
	v_mfma_f32_16x16x32_bf16 v[120:123], v[166:169], v[190:193], v[120:123]
	v_mfma_f32_16x16x32_bf16 v[116:119], v[144:147], v[198:201], v[116:119]
	v_mfma_f32_16x16x32_bf16 v[112:115], v[166:169], v[198:201], v[112:115]
	v_mfma_f32_16x16x32_bf16 v[92:95], v[144:147], v[206:209], v[92:95]
	v_mfma_f32_16x16x32_bf16 v[88:91], v[166:169], v[206:209], v[88:91]
	v_mfma_f32_16x16x32_bf16 v[76:79], v[144:147], v[214:217], v[76:79]
	v_mfma_f32_16x16x32_bf16 v[72:75], v[166:169], v[214:217], v[72:75]
	v_mfma_f32_16x16x32_bf16 v[124:127], v[162:165], v[194:197], v[124:127]
	v_mfma_f32_16x16x32_bf16 v[120:123], v[170:173], v[194:197], v[120:123]
	v_mfma_f32_16x16x32_bf16 v[116:119], v[162:165], v[202:205], v[116:119]
	v_mfma_f32_16x16x32_bf16 v[112:115], v[170:173], v[202:205], v[112:115]
	v_mfma_f32_16x16x32_bf16 v[92:95], v[162:165], v[210:213], v[92:95]
	v_mfma_f32_16x16x32_bf16 v[88:91], v[170:173], v[210:213], v[88:91]
	v_mfma_f32_16x16x32_bf16 v[76:79], v[162:165], v[218:221], v[76:79]
	v_mfma_f32_16x16x32_bf16 v[72:75], v[170:173], v[218:221], v[72:75]
	s_setprio 0
	s_setprio 3
	v_mfma_f32_16x16x32_bf16 v[108:111], v[174:177], v[190:193], v[108:111]
	v_mfma_f32_16x16x32_bf16 v[104:107], v[182:185], v[190:193], v[104:107]
	v_mfma_f32_16x16x32_bf16 v[100:103], v[174:177], v[198:201], v[100:103]
	v_mfma_f32_16x16x32_bf16 v[96:99], v[182:185], v[198:201], v[96:99]
	v_mfma_f32_16x16x32_bf16 v[84:87], v[174:177], v[206:209], v[84:87]
	v_mfma_f32_16x16x32_bf16 v[80:83], v[182:185], v[206:209], v[80:83]
	v_mfma_f32_16x16x32_bf16 v[68:71], v[174:177], v[214:217], v[68:71]
	v_mfma_f32_16x16x32_bf16 v[64:67], v[182:185], v[214:217], v[64:67]
	v_mfma_f32_16x16x32_bf16 v[108:111], v[178:181], v[194:197], v[108:111]
	v_mfma_f32_16x16x32_bf16 v[104:107], v[186:189], v[194:197], v[104:107]
	v_mfma_f32_16x16x32_bf16 v[100:103], v[178:181], v[202:205], v[100:103]
	v_mfma_f32_16x16x32_bf16 v[96:99], v[186:189], v[202:205], v[96:99]
	v_mfma_f32_16x16x32_bf16 v[84:87], v[178:181], v[210:213], v[84:87]
	v_mfma_f32_16x16x32_bf16 v[80:83], v[186:189], v[210:213], v[80:83]
	v_mfma_f32_16x16x32_bf16 v[68:71], v[178:181], v[218:221], v[68:71]
	v_mfma_f32_16x16x32_bf16 v[64:67], v[186:189], v[218:221], v[64:67]
	s_setprio 0
	s_barrier
	s_add_u32 s98, s50, s10
	s_addc_u32 s99, s51, s11
	s_add_u32 s100, s58, s10
	s_addc_u32 s101, s59, s11
	s_add_i32 s77, s68, s89
	s_mov_b32 m0, s77
	ds_read_b128 v[190:193], v160 offset:16384
	ds_read_b128 v[194:197], v160 offset:17408
	ds_read_b128 v[198:201], v160 offset:18432
	ds_read_b128 v[202:205], v160 offset:19456
	ds_read_b128 v[206:209], v160 offset:20480
	ds_read_b128 v[210:213], v160 offset:21504
	ds_read_b128 v[214:217], v160 offset:22528
	ds_read_b128 v[218:221], v160 offset:23552
	global_load_lds_dwordx4 v128, s[50:51]
	s_add_i32 m0, s77, 0x2000
	s_add_u32 s78, s50, 0x80000
	s_addc_u32 s79, s51, 0
	s_add_i32 s77, s69, s89
	global_load_lds_dwordx4 v130, s[50:51]
	s_mov_b32 m0, s77
	s_nop 0
	global_load_lds_dwordx4 v128, s[78:79]
	s_add_i32 m0, s77, 0x2000
	s_nop 0
	global_load_lds_dwordx4 v130, s[78:79]
	s_mov_b32 m0, s47
	s_nop 0
	global_load_lds_dwordx4 v134, s[58:59]
	s_mov_b32 m0, s56
	s_nop 0
	global_load_lds_dwordx4 v132, s[58:59]
	s_waitcnt vmcnt(8)
	s_waitcnt lgkmcnt(0)
	s_barrier
	s_setprio 3
	s_waitcnt lgkmcnt(0)
	v_mfma_f32_16x16x32_bf16 v[60:63], v[144:147], v[190:193], v[60:63]
	v_mfma_f32_16x16x32_bf16 v[56:59], v[166:169], v[190:193], v[56:59]
	v_mfma_f32_16x16x32_bf16 v[44:47], v[144:147], v[198:201], v[44:47]
	v_mfma_f32_16x16x32_bf16 v[40:43], v[166:169], v[198:201], v[40:43]
	v_mfma_f32_16x16x32_bf16 v[28:31], v[144:147], v[206:209], v[28:31]
	v_mfma_f32_16x16x32_bf16 v[24:27], v[166:169], v[206:209], v[24:27]
	v_mfma_f32_16x16x32_bf16 v[12:15], v[144:147], v[214:217], v[12:15]
	v_mfma_f32_16x16x32_bf16 v[8:11], v[166:169], v[214:217], v[8:11]
	v_mfma_f32_16x16x32_bf16 v[60:63], v[162:165], v[194:197], v[60:63]
	v_mfma_f32_16x16x32_bf16 v[56:59], v[170:173], v[194:197], v[56:59]
	v_mfma_f32_16x16x32_bf16 v[44:47], v[162:165], v[202:205], v[44:47]
	v_mfma_f32_16x16x32_bf16 v[40:43], v[170:173], v[202:205], v[40:43]
	v_mfma_f32_16x16x32_bf16 v[28:31], v[162:165], v[210:213], v[28:31]
	v_mfma_f32_16x16x32_bf16 v[24:27], v[170:173], v[210:213], v[24:27]
	v_mfma_f32_16x16x32_bf16 v[12:15], v[162:165], v[218:221], v[12:15]
	v_mfma_f32_16x16x32_bf16 v[8:11], v[170:173], v[218:221], v[8:11]
	s_setprio 0
	s_setprio 3
	v_mfma_f32_16x16x32_bf16 v[52:55], v[174:177], v[190:193], v[52:55]
	v_mfma_f32_16x16x32_bf16 v[48:51], v[182:185], v[190:193], v[48:51]
	v_mfma_f32_16x16x32_bf16 v[36:39], v[174:177], v[198:201], v[36:39]
	v_mfma_f32_16x16x32_bf16 v[32:35], v[182:185], v[198:201], v[32:35]
	v_mfma_f32_16x16x32_bf16 v[20:23], v[174:177], v[206:209], v[20:23]
	v_mfma_f32_16x16x32_bf16 v[16:19], v[182:185], v[206:209], v[16:19]
	v_mfma_f32_16x16x32_bf16 v[4:7], v[174:177], v[214:217], v[4:7]
	v_mfma_f32_16x16x32_bf16 v[0:3], v[182:185], v[214:217], v[0:3]
	v_mfma_f32_16x16x32_bf16 v[52:55], v[178:181], v[194:197], v[52:55]
	v_mfma_f32_16x16x32_bf16 v[48:51], v[186:189], v[194:197], v[48:51]
	v_mfma_f32_16x16x32_bf16 v[36:39], v[178:181], v[202:205], v[36:39]
	v_mfma_f32_16x16x32_bf16 v[32:35], v[186:189], v[202:205], v[32:35]
	v_mfma_f32_16x16x32_bf16 v[20:23], v[178:181], v[210:213], v[20:23]
	v_mfma_f32_16x16x32_bf16 v[16:19], v[186:189], v[210:213], v[16:19]
	v_mfma_f32_16x16x32_bf16 v[4:7], v[178:181], v[218:221], v[4:7]
	v_mfma_f32_16x16x32_bf16 v[0:3], v[186:189], v[218:221], v[0:3]
	s_setprio 0
	s_barrier
	s_add_i32 s77, 0, 0x18000
	s_add_i32 s78, 0, 0x1c000
	ds_read_b128 v[144:147], v148
	ds_read_b128 v[162:165], v148 offset:1024
	ds_read_b128 v[166:169], v148 offset:2048
	ds_read_b128 v[170:173], v148 offset:3072
	ds_read_b128 v[174:177], v149
	ds_read_b128 v[178:181], v149 offset:1024
	ds_read_b128 v[182:185], v149 offset:2048
	ds_read_b128 v[186:189], v149 offset:3072
	s_add_u32 s58, s58, 0x80000
	s_addc_u32 s59, s59, 0
	s_mov_b32 m0, s57
	ds_read_b128 v[190:193], v160 offset:32768
	ds_read_b128 v[194:197], v160 offset:33792
	ds_read_b128 v[198:201], v160 offset:34816
	ds_read_b128 v[202:205], v160 offset:35840
	ds_read_b128 v[206:209], v160 offset:36864
	ds_read_b128 v[210:213], v160 offset:37888
	ds_read_b128 v[214:217], v160 offset:38912
	ds_read_b128 v[218:221], v160 offset:39936
	global_load_lds_dwordx4 v134, s[58:59]
	s_mov_b32 m0, s61
	s_nop 0
	global_load_lds_dwordx4 v132, s[58:59]
	s_waitcnt vmcnt(8)
	s_waitcnt lgkmcnt(0)
	s_barrier
	s_setprio 3
	s_waitcnt lgkmcnt(0)
	v_mfma_f32_16x16x32_bf16 v[124:127], v[144:147], v[190:193], v[124:127]
	v_mfma_f32_16x16x32_bf16 v[120:123], v[166:169], v[190:193], v[120:123]
	v_mfma_f32_16x16x32_bf16 v[116:119], v[144:147], v[198:201], v[116:119]
	v_mfma_f32_16x16x32_bf16 v[112:115], v[166:169], v[198:201], v[112:115]
	v_mfma_f32_16x16x32_bf16 v[92:95], v[144:147], v[206:209], v[92:95]
	v_mfma_f32_16x16x32_bf16 v[88:91], v[166:169], v[206:209], v[88:91]
	v_mfma_f32_16x16x32_bf16 v[76:79], v[144:147], v[214:217], v[76:79]
	v_mfma_f32_16x16x32_bf16 v[72:75], v[166:169], v[214:217], v[72:75]
	v_mfma_f32_16x16x32_bf16 v[124:127], v[162:165], v[194:197], v[124:127]
	v_mfma_f32_16x16x32_bf16 v[120:123], v[170:173], v[194:197], v[120:123]
	v_mfma_f32_16x16x32_bf16 v[116:119], v[162:165], v[202:205], v[116:119]
	v_mfma_f32_16x16x32_bf16 v[112:115], v[170:173], v[202:205], v[112:115]
	v_mfma_f32_16x16x32_bf16 v[92:95], v[162:165], v[210:213], v[92:95]
	v_mfma_f32_16x16x32_bf16 v[88:91], v[170:173], v[210:213], v[88:91]
	v_mfma_f32_16x16x32_bf16 v[76:79], v[162:165], v[218:221], v[76:79]
	v_mfma_f32_16x16x32_bf16 v[72:75], v[170:173], v[218:221], v[72:75]
	s_setprio 0
	s_setprio 3
	v_mfma_f32_16x16x32_bf16 v[108:111], v[174:177], v[190:193], v[108:111]
	v_mfma_f32_16x16x32_bf16 v[104:107], v[182:185], v[190:193], v[104:107]
	v_mfma_f32_16x16x32_bf16 v[100:103], v[174:177], v[198:201], v[100:103]
	v_mfma_f32_16x16x32_bf16 v[96:99], v[182:185], v[198:201], v[96:99]
	v_mfma_f32_16x16x32_bf16 v[84:87], v[174:177], v[206:209], v[84:87]
	v_mfma_f32_16x16x32_bf16 v[80:83], v[182:185], v[206:209], v[80:83]
	v_mfma_f32_16x16x32_bf16 v[68:71], v[174:177], v[214:217], v[68:71]
	v_mfma_f32_16x16x32_bf16 v[64:67], v[182:185], v[214:217], v[64:67]
	v_mfma_f32_16x16x32_bf16 v[108:111], v[178:181], v[194:197], v[108:111]
	v_mfma_f32_16x16x32_bf16 v[104:107], v[186:189], v[194:197], v[104:107]
	v_mfma_f32_16x16x32_bf16 v[100:103], v[178:181], v[202:205], v[100:103]
	v_mfma_f32_16x16x32_bf16 v[96:99], v[186:189], v[202:205], v[96:99]
	v_mfma_f32_16x16x32_bf16 v[84:87], v[178:181], v[210:213], v[84:87]
	v_mfma_f32_16x16x32_bf16 v[80:83], v[186:189], v[210:213], v[80:83]
	v_mfma_f32_16x16x32_bf16 v[68:71], v[178:181], v[218:221], v[68:71]
	v_mfma_f32_16x16x32_bf16 v[64:67], v[186:189], v[218:221], v[64:67]
	s_setprio 0
	s_barrier
	s_add_i32 s58, s77, s89
	s_mov_b32 m0, s58
	ds_read_b128 v[190:193], v160 offset:49152
	ds_read_b128 v[194:197], v160 offset:50176
	ds_read_b128 v[198:201], v160 offset:51200
	ds_read_b128 v[202:205], v160 offset:52224
	ds_read_b128 v[206:209], v160 offset:53248
	ds_read_b128 v[210:213], v160 offset:54272
	ds_read_b128 v[214:217], v160 offset:55296
	ds_read_b128 v[218:221], v160 offset:56320
	global_load_lds_dwordx4 v128, s[98:99]
	s_add_i32 m0, s58, 0x2000
	s_add_u32 s50, s50, 0x80080
	s_addc_u32 s51, s51, 0
	s_add_i32 s58, s78, s89
	global_load_lds_dwordx4 v130, s[98:99]
	s_mov_b32 m0, s58
	s_nop 0
	global_load_lds_dwordx4 v128, s[50:51]
	s_add_i32 m0, s58, 0x2000
	s_nop 0
	global_load_lds_dwordx4 v130, s[50:51]
	s_mov_b32 m0, s64
	s_nop 0
	global_load_lds_dwordx4 v134, s[100:101]
	s_mov_b32 m0, s65
	s_nop 0
	global_load_lds_dwordx4 v132, s[100:101]
	s_waitcnt vmcnt(8)
	s_waitcnt lgkmcnt(0)
	s_barrier
	s_setprio 3
	s_waitcnt lgkmcnt(0)
	v_mfma_f32_16x16x32_bf16 v[60:63], v[144:147], v[190:193], v[60:63]
	v_mfma_f32_16x16x32_bf16 v[56:59], v[166:169], v[190:193], v[56:59]
	v_mfma_f32_16x16x32_bf16 v[44:47], v[144:147], v[198:201], v[44:47]
	v_mfma_f32_16x16x32_bf16 v[40:43], v[166:169], v[198:201], v[40:43]
	v_mfma_f32_16x16x32_bf16 v[28:31], v[144:147], v[206:209], v[28:31]
	v_mfma_f32_16x16x32_bf16 v[24:27], v[166:169], v[206:209], v[24:27]
	v_mfma_f32_16x16x32_bf16 v[12:15], v[144:147], v[214:217], v[12:15]
	v_mfma_f32_16x16x32_bf16 v[8:11], v[166:169], v[214:217], v[8:11]
	v_mfma_f32_16x16x32_bf16 v[60:63], v[162:165], v[194:197], v[60:63]
	v_mfma_f32_16x16x32_bf16 v[56:59], v[170:173], v[194:197], v[56:59]
	v_mfma_f32_16x16x32_bf16 v[44:47], v[162:165], v[202:205], v[44:47]
	v_mfma_f32_16x16x32_bf16 v[40:43], v[170:173], v[202:205], v[40:43]
	v_mfma_f32_16x16x32_bf16 v[28:31], v[162:165], v[210:213], v[28:31]
	v_mfma_f32_16x16x32_bf16 v[24:27], v[170:173], v[210:213], v[24:27]
	v_mfma_f32_16x16x32_bf16 v[12:15], v[162:165], v[218:221], v[12:15]
	v_mfma_f32_16x16x32_bf16 v[8:11], v[170:173], v[218:221], v[8:11]
	s_setprio 0
	s_setprio 3
	v_mfma_f32_16x16x32_bf16 v[52:55], v[174:177], v[190:193], v[52:55]
	v_mfma_f32_16x16x32_bf16 v[48:51], v[182:185], v[190:193], v[48:51]
	v_mfma_f32_16x16x32_bf16 v[36:39], v[174:177], v[198:201], v[36:39]
	v_mfma_f32_16x16x32_bf16 v[32:35], v[182:185], v[198:201], v[32:35]
	v_mfma_f32_16x16x32_bf16 v[20:23], v[174:177], v[206:209], v[20:23]
	v_mfma_f32_16x16x32_bf16 v[16:19], v[182:185], v[206:209], v[16:19]
	v_mfma_f32_16x16x32_bf16 v[4:7], v[174:177], v[214:217], v[4:7]
	v_mfma_f32_16x16x32_bf16 v[0:3], v[182:185], v[214:217], v[0:3]
	v_mfma_f32_16x16x32_bf16 v[52:55], v[178:181], v[194:197], v[52:55]
	v_mfma_f32_16x16x32_bf16 v[48:51], v[186:189], v[194:197], v[48:51]
	v_mfma_f32_16x16x32_bf16 v[36:39], v[178:181], v[202:205], v[36:39]
	v_mfma_f32_16x16x32_bf16 v[32:35], v[186:189], v[202:205], v[32:35]
	v_mfma_f32_16x16x32_bf16 v[20:23], v[178:181], v[210:213], v[20:23]
	v_mfma_f32_16x16x32_bf16 v[16:19], v[186:189], v[210:213], v[16:19]
	v_mfma_f32_16x16x32_bf16 v[4:7], v[178:181], v[218:221], v[4:7]
	v_mfma_f32_16x16x32_bf16 v[0:3], v[186:189], v[218:221], v[0:3]
	s_setprio 0
	s_barrier
	s_add_i32 s76, s76, 2
	s_add_u32 s48, s48, 0x100
	s_addc_u32 s49, s49, 0
	s_add_u32 s74, s74, 0x100
	s_addc_u32 s75, s75, 0
	s_cmp_gt_u32 s76, 29
	s_cbranch_scc0 .LBB0_151
	s_and_b64 vcc, exec, s[12:13]
	s_cbranch_vccz .LBB0_154
	s_barrier

.LBB0_259:
	s_add_u32 s78, s64, 0x100
	v_mov_b32_e32 v0, 0
	s_addc_u32 s79, s65, 0
	s_mov_b32 s80, -2
	s_waitcnt lgkmcnt(0)
	v_mov_b32_e32 v1, v0
	v_mov_b32_e32 v2, v0
	v_mov_b32_e32 v3, v0
	v_mov_b32_e32 v4, v0
	v_mov_b32_e32 v5, v0
	v_mov_b32_e32 v6, v0
	v_mov_b32_e32 v7, v0
	v_mov_b32_e32 v16, v0
	v_mov_b32_e32 v17, v0
	v_mov_b32_e32 v18, v0
	v_mov_b32_e32 v19, v0
	v_mov_b32_e32 v20, v0
	v_mov_b32_e32 v21, v0
	v_mov_b32_e32 v22, v0
	v_mov_b32_e32 v23, v0
	v_mov_b32_e32 v32, v0
	v_mov_b32_e32 v33, v0
	v_mov_b32_e32 v34, v0
	v_mov_b32_e32 v35, v0
	v_mov_b32_e32 v36, v0
	v_mov_b32_e32 v37, v0
	v_mov_b32_e32 v38, v0
	v_mov_b32_e32 v39, v0
	v_mov_b32_e32 v48, v0
	v_mov_b32_e32 v49, v0
	v_mov_b32_e32 v50, v0
	v_mov_b32_e32 v51, v0
	v_mov_b32_e32 v52, v0
	v_mov_b32_e32 v53, v0
	v_mov_b32_e32 v54, v0
	v_mov_b32_e32 v55, v0
	v_mov_b32_e32 v8, v0
	v_mov_b32_e32 v9, v0
	v_mov_b32_e32 v10, v0
	v_mov_b32_e32 v11, v0
	v_mov_b32_e32 v12, v0
	v_mov_b32_e32 v13, v0
	v_mov_b32_e32 v14, v0
	v_mov_b32_e32 v15, v0
	v_mov_b32_e32 v24, v0
	v_mov_b32_e32 v25, v0
	v_mov_b32_e32 v26, v0
	v_mov_b32_e32 v27, v0
	v_mov_b32_e32 v28, v0
	v_mov_b32_e32 v29, v0
	v_mov_b32_e32 v30, v0
	v_mov_b32_e32 v31, v0
	v_mov_b32_e32 v40, v0
	v_mov_b32_e32 v41, v0
	v_mov_b32_e32 v42, v0
	v_mov_b32_e32 v43, v0
	v_mov_b32_e32 v44, v0
	v_mov_b32_e32 v45, v0
	v_mov_b32_e32 v46, v0
	v_mov_b32_e32 v47, v0
	v_mov_b32_e32 v56, v0
	v_mov_b32_e32 v57, v0
	v_mov_b32_e32 v58, v0
	v_mov_b32_e32 v59, v0
	v_mov_b32_e32 v60, v0
	v_mov_b32_e32 v61, v0
	v_mov_b32_e32 v62, v0
	v_mov_b32_e32 v63, v0
	v_mov_b32_e32 v64, v0
	v_mov_b32_e32 v65, v0
	v_mov_b32_e32 v66, v0
	v_mov_b32_e32 v67, v0
	v_mov_b32_e32 v68, v0
	v_mov_b32_e32 v69, v0
	v_mov_b32_e32 v70, v0
	v_mov_b32_e32 v71, v0
	v_mov_b32_e32 v80, v0
	v_mov_b32_e32 v81, v0
	v_mov_b32_e32 v82, v0
	v_mov_b32_e32 v83, v0
	v_mov_b32_e32 v84, v0
	v_mov_b32_e32 v85, v0
	v_mov_b32_e32 v86, v0
	v_mov_b32_e32 v87, v0
	v_mov_b32_e32 v96, v0
	v_mov_b32_e32 v97, v0
	v_mov_b32_e32 v98, v0
	v_mov_b32_e32 v99, v0
	v_mov_b32_e32 v100, v0
	v_mov_b32_e32 v101, v0
	v_mov_b32_e32 v102, v0
	v_mov_b32_e32 v103, v0
	v_mov_b32_e32 v112, v0
	v_mov_b32_e32 v113, v0
	v_mov_b32_e32 v114, v0
	v_mov_b32_e32 v115, v0
	v_mov_b32_e32 v116, v0
	v_mov_b32_e32 v117, v0
	v_mov_b32_e32 v118, v0
	v_mov_b32_e32 v119, v0
	v_mov_b32_e32 v72, v0
	v_mov_b32_e32 v73, v0
	v_mov_b32_e32 v74, v0
	v_mov_b32_e32 v75, v0
	v_mov_b32_e32 v76, v0
	v_mov_b32_e32 v77, v0
	v_mov_b32_e32 v78, v0
	v_mov_b32_e32 v79, v0
	v_mov_b32_e32 v88, v0
	v_mov_b32_e32 v89, v0
	v_mov_b32_e32 v90, v0
	v_mov_b32_e32 v91, v0
	v_mov_b32_e32 v92, v0
	v_mov_b32_e32 v93, v0
	v_mov_b32_e32 v94, v0
	v_mov_b32_e32 v95, v0
	v_mov_b32_e32 v104, v0
	v_mov_b32_e32 v105, v0
	v_mov_b32_e32 v106, v0
	v_mov_b32_e32 v107, v0
	v_mov_b32_e32 v108, v0
	v_mov_b32_e32 v109, v0
	v_mov_b32_e32 v110, v0
	v_mov_b32_e32 v111, v0
	v_mov_b32_e32 v120, v0
	v_mov_b32_e32 v121, v0
	v_mov_b32_e32 v122, v0
	v_mov_b32_e32 v123, v0
	v_mov_b32_e32 v124, v0
	v_mov_b32_e32 v125, v0
	v_mov_b32_e32 v126, v0
	v_mov_b32_e32 v127, v0
	v_add_u32_e32 v212, 0x18000, v177
	v_add_u32_e32 v213, 0x1c000, v177
.LBB0_260:
	ds_read_b128 v[140:143], v181
	ds_read_b128 v[144:147], v181 offset:1024
	ds_read_b128 v[148:151], v181 offset:2048
	ds_read_b128 v[152:155], v181 offset:3072
	ds_read_b128 v[156:159], v182
	ds_read_b128 v[160:163], v182 offset:1024
	ds_read_b128 v[164:167], v182 offset:2048
	ds_read_b128 v[168:171], v182 offset:3072
	s_add_u32 s64, s50, 0x100
	s_addc_u32 s65, s51, 0
	s_cmpk_eq_i32 s80, 0x54
	s_cselect_b32 s71, s11, s65
	s_cselect_b32 s70, s10, s64
	s_cselect_b32 s69, s49, s79
	s_cselect_b32 s68, s48, s78
	s_add_i32 m0, s4, 0xc000
	ds_read_b128 v[172:175], v183
	ds_read_b128 v[184:187], v183 offset:1024
	ds_read_b128 v[188:191], v183 offset:2048
	ds_read_b128 v[192:195], v183 offset:3072
	ds_read_b128 v[196:199], v183 offset:4096
	ds_read_b128 v[200:203], v183 offset:5120
	ds_read_b128 v[204:207], v183 offset:6144
	ds_read_b128 v[208:211], v183 offset:7168
	global_load_lds_dwordx4 v132, s[50:51]
	s_add_i32 m0, s4, 0xe000
	s_nop 0
	global_load_lds_dwordx4 v134, s[50:51]
	s_waitcnt vmcnt(8)
	s_waitcnt lgkmcnt(0)
	s_barrier
	s_setprio 3
	s_waitcnt lgkmcnt(0)
	v_mfma_f32_16x16x32_bf16 v[124:127], v[140:143], v[172:175], v[124:127]
	v_mfma_f32_16x16x32_bf16 v[120:123], v[148:151], v[172:175], v[120:123]
	v_mfma_f32_16x16x32_bf16 v[108:111], v[140:143], v[188:191], v[108:111]
	v_mfma_f32_16x16x32_bf16 v[104:107], v[148:151], v[188:191], v[104:107]
	v_mfma_f32_16x16x32_bf16 v[92:95], v[140:143], v[196:199], v[92:95]
	v_mfma_f32_16x16x32_bf16 v[88:91], v[148:151], v[196:199], v[88:91]
	v_mfma_f32_16x16x32_bf16 v[76:79], v[140:143], v[204:207], v[76:79]
	v_mfma_f32_16x16x32_bf16 v[72:75], v[148:151], v[204:207], v[72:75]
	v_mfma_f32_16x16x32_bf16 v[124:127], v[144:147], v[184:187], v[124:127]
	v_mfma_f32_16x16x32_bf16 v[120:123], v[152:155], v[184:187], v[120:123]
	v_mfma_f32_16x16x32_bf16 v[108:111], v[144:147], v[192:195], v[108:111]
	v_mfma_f32_16x16x32_bf16 v[104:107], v[152:155], v[192:195], v[104:107]
	v_mfma_f32_16x16x32_bf16 v[92:95], v[144:147], v[200:203], v[92:95]
	v_mfma_f32_16x16x32_bf16 v[88:91], v[152:155], v[200:203], v[88:91]
	v_mfma_f32_16x16x32_bf16 v[76:79], v[144:147], v[208:211], v[76:79]
	v_mfma_f32_16x16x32_bf16 v[72:75], v[152:155], v[208:211], v[72:75]
	s_setprio 0
	s_setprio 3
	v_mfma_f32_16x16x32_bf16 v[116:119], v[156:159], v[172:175], v[116:119]
	v_mfma_f32_16x16x32_bf16 v[112:115], v[164:167], v[172:175], v[112:115]
	v_mfma_f32_16x16x32_bf16 v[100:103], v[156:159], v[188:191], v[100:103]
	v_mfma_f32_16x16x32_bf16 v[96:99], v[164:167], v[188:191], v[96:99]
	v_mfma_f32_16x16x32_bf16 v[84:87], v[156:159], v[196:199], v[84:87]
	v_mfma_f32_16x16x32_bf16 v[80:83], v[164:167], v[196:199], v[80:83]
	v_mfma_f32_16x16x32_bf16 v[68:71], v[156:159], v[204:207], v[68:71]
	v_mfma_f32_16x16x32_bf16 v[64:67], v[164:167], v[204:207], v[64:67]
	v_mfma_f32_16x16x32_bf16 v[116:119], v[160:163], v[184:187], v[116:119]
	v_mfma_f32_16x16x32_bf16 v[112:115], v[168:171], v[184:187], v[112:115]
	v_mfma_f32_16x16x32_bf16 v[100:103], v[160:163], v[192:195], v[100:103]
	v_mfma_f32_16x16x32_bf16 v[96:99], v[168:171], v[192:195], v[96:99]
	v_mfma_f32_16x16x32_bf16 v[84:87], v[160:163], v[200:203], v[84:87]
	v_mfma_f32_16x16x32_bf16 v[80:83], v[168:171], v[200:203], v[80:83]
	v_mfma_f32_16x16x32_bf16 v[68:71], v[160:163], v[208:211], v[68:71]
	v_mfma_f32_16x16x32_bf16 v[64:67], v[168:171], v[208:211], v[64:67]
	s_setprio 0
	s_barrier
	s_add_u32 s98, s68, s16
	s_addc_u32 s99, s69, s17
	s_add_u32 s100, s70, s16
	s_addc_u32 s101, s71, s17
	s_add_i32 s50, s72, s89
	s_mov_b32 m0, s50
	ds_read_b128 v[172:175], v183 offset:16384
	ds_read_b128 v[184:187], v183 offset:17408
	ds_read_b128 v[188:191], v183 offset:18432
	ds_read_b128 v[192:195], v183 offset:19456
	ds_read_b128 v[196:199], v183 offset:20480
	ds_read_b128 v[200:203], v183 offset:21504
	ds_read_b128 v[204:207], v183 offset:22528
	ds_read_b128 v[208:211], v183 offset:23552
	global_load_lds_dwordx4 v128, s[68:69]
	s_add_i32 m0, s50, 0x2000
	s_add_u32 s50, s68, 0x160000
	s_addc_u32 s51, s69, 0
	s_add_i32 s81, s73, s89
	global_load_lds_dwordx4 v130, s[68:69]
	s_mov_b32 m0, s81
	s_nop 0
	global_load_lds_dwordx4 v128, s[50:51]
	s_add_i32 m0, s81, 0x2000
	s_nop 0
	global_load_lds_dwordx4 v130, s[50:51]
	s_mov_b32 m0, s4
	s_nop 0
	global_load_lds_dwordx4 v128, s[70:71]
	s_mov_b32 m0, s5
	s_nop 0
	global_load_lds_dwordx4 v130, s[70:71]
	s_waitcnt vmcnt(8)
	s_waitcnt lgkmcnt(0)
	s_barrier
	s_setprio 3
	s_waitcnt lgkmcnt(0)
	v_mfma_f32_16x16x32_bf16 v[60:63], v[140:143], v[172:175], v[60:63]
	v_mfma_f32_16x16x32_bf16 v[56:59], v[148:151], v[172:175], v[56:59]
	v_mfma_f32_16x16x32_bf16 v[44:47], v[140:143], v[188:191], v[44:47]
	v_mfma_f32_16x16x32_bf16 v[40:43], v[148:151], v[188:191], v[40:43]
	v_mfma_f32_16x16x32_bf16 v[28:31], v[140:143], v[196:199], v[28:31]
	v_mfma_f32_16x16x32_bf16 v[24:27], v[148:151], v[196:199], v[24:27]
	v_mfma_f32_16x16x32_bf16 v[12:15], v[140:143], v[204:207], v[12:15]
	v_mfma_f32_16x16x32_bf16 v[8:11], v[148:151], v[204:207], v[8:11]
	v_mfma_f32_16x16x32_bf16 v[60:63], v[144:147], v[184:187], v[60:63]
	v_mfma_f32_16x16x32_bf16 v[56:59], v[152:155], v[184:187], v[56:59]
	v_mfma_f32_16x16x32_bf16 v[44:47], v[144:147], v[192:195], v[44:47]
	v_mfma_f32_16x16x32_bf16 v[40:43], v[152:155], v[192:195], v[40:43]
	v_mfma_f32_16x16x32_bf16 v[28:31], v[144:147], v[200:203], v[28:31]
	v_mfma_f32_16x16x32_bf16 v[24:27], v[152:155], v[200:203], v[24:27]
	v_mfma_f32_16x16x32_bf16 v[12:15], v[144:147], v[208:211], v[12:15]
	v_mfma_f32_16x16x32_bf16 v[8:11], v[152:155], v[208:211], v[8:11]
	s_setprio 0
	s_setprio 3
	v_mfma_f32_16x16x32_bf16 v[52:55], v[156:159], v[172:175], v[52:55]
	v_mfma_f32_16x16x32_bf16 v[48:51], v[164:167], v[172:175], v[48:51]
	v_mfma_f32_16x16x32_bf16 v[36:39], v[156:159], v[188:191], v[36:39]
	v_mfma_f32_16x16x32_bf16 v[32:35], v[164:167], v[188:191], v[32:35]
	v_mfma_f32_16x16x32_bf16 v[20:23], v[156:159], v[196:199], v[20:23]
	v_mfma_f32_16x16x32_bf16 v[16:19], v[164:167], v[196:199], v[16:19]
	v_mfma_f32_16x16x32_bf16 v[4:7], v[156:159], v[204:207], v[4:7]
	v_mfma_f32_16x16x32_bf16 v[0:3], v[164:167], v[204:207], v[0:3]
	v_mfma_f32_16x16x32_bf16 v[52:55], v[160:163], v[184:187], v[52:55]
	v_mfma_f32_16x16x32_bf16 v[48:51], v[168:171], v[184:187], v[48:51]
	v_mfma_f32_16x16x32_bf16 v[36:39], v[160:163], v[192:195], v[36:39]
	v_mfma_f32_16x16x32_bf16 v[32:35], v[168:171], v[192:195], v[32:35]
	v_mfma_f32_16x16x32_bf16 v[20:23], v[160:163], v[200:203], v[20:23]
	v_mfma_f32_16x16x32_bf16 v[16:19], v[168:171], v[200:203], v[16:19]
	v_mfma_f32_16x16x32_bf16 v[4:7], v[160:163], v[208:211], v[4:7]
	v_mfma_f32_16x16x32_bf16 v[0:3], v[168:171], v[208:211], v[0:3]
	s_setprio 0
	s_barrier
	s_add_i32 s81, 0, 0x18000
	s_add_i32 s82, 0, 0x1c000
	ds_read_b128 v[140:143], v212
	ds_read_b128 v[144:147], v212 offset:1024
	ds_read_b128 v[148:151], v212 offset:2048
	ds_read_b128 v[152:155], v212 offset:3072
	ds_read_b128 v[156:159], v213
	ds_read_b128 v[160:163], v213 offset:1024
	ds_read_b128 v[164:167], v213 offset:2048
	ds_read_b128 v[168:171], v213 offset:3072
	s_add_u32 s50, s70, 0x160000
	s_addc_u32 s51, s71, 0
	s_mov_b32 m0, s28
	ds_read_b128 v[172:175], v183 offset:32768
	ds_read_b128 v[184:187], v183 offset:33792
	ds_read_b128 v[188:191], v183 offset:34816
	ds_read_b128 v[192:195], v183 offset:35840
	ds_read_b128 v[196:199], v183 offset:36864
	ds_read_b128 v[200:203], v183 offset:37888
	ds_read_b128 v[204:207], v183 offset:38912
	ds_read_b128 v[208:211], v183 offset:39936
	global_load_lds_dwordx4 v128, s[50:51]
	s_mov_b32 m0, s29
	s_nop 0
	global_load_lds_dwordx4 v130, s[50:51]
	s_waitcnt vmcnt(8)
	s_waitcnt lgkmcnt(0)
	s_barrier
	s_setprio 3
	s_waitcnt lgkmcnt(0)
	v_mfma_f32_16x16x32_bf16 v[124:127], v[140:143], v[172:175], v[124:127]
	v_mfma_f32_16x16x32_bf16 v[120:123], v[148:151], v[172:175], v[120:123]
	v_mfma_f32_16x16x32_bf16 v[108:111], v[140:143], v[188:191], v[108:111]
	v_mfma_f32_16x16x32_bf16 v[104:107], v[148:151], v[188:191], v[104:107]
	v_mfma_f32_16x16x32_bf16 v[92:95], v[140:143], v[196:199], v[92:95]
	v_mfma_f32_16x16x32_bf16 v[88:91], v[148:151], v[196:199], v[88:91]
	v_mfma_f32_16x16x32_bf16 v[76:79], v[140:143], v[204:207], v[76:79]
	v_mfma_f32_16x16x32_bf16 v[72:75], v[148:151], v[204:207], v[72:75]
	v_mfma_f32_16x16x32_bf16 v[124:127], v[144:147], v[184:187], v[124:127]
	v_mfma_f32_16x16x32_bf16 v[120:123], v[152:155], v[184:187], v[120:123]
	v_mfma_f32_16x16x32_bf16 v[108:111], v[144:147], v[192:195], v[108:111]
	v_mfma_f32_16x16x32_bf16 v[104:107], v[152:155], v[192:195], v[104:107]
	v_mfma_f32_16x16x32_bf16 v[92:95], v[144:147], v[200:203], v[92:95]
	v_mfma_f32_16x16x32_bf16 v[88:91], v[152:155], v[200:203], v[88:91]
	v_mfma_f32_16x16x32_bf16 v[76:79], v[144:147], v[208:211], v[76:79]
	v_mfma_f32_16x16x32_bf16 v[72:75], v[152:155], v[208:211], v[72:75]
	s_setprio 0
	s_setprio 3
	v_mfma_f32_16x16x32_bf16 v[116:119], v[156:159], v[172:175], v[116:119]
	v_mfma_f32_16x16x32_bf16 v[112:115], v[164:167], v[172:175], v[112:115]
	v_mfma_f32_16x16x32_bf16 v[100:103], v[156:159], v[188:191], v[100:103]
	v_mfma_f32_16x16x32_bf16 v[96:99], v[164:167], v[188:191], v[96:99]
	v_mfma_f32_16x16x32_bf16 v[84:87], v[156:159], v[196:199], v[84:87]
	v_mfma_f32_16x16x32_bf16 v[80:83], v[164:167], v[196:199], v[80:83]
	v_mfma_f32_16x16x32_bf16 v[68:71], v[156:159], v[204:207], v[68:71]
	v_mfma_f32_16x16x32_bf16 v[64:67], v[164:167], v[204:207], v[64:67]
	v_mfma_f32_16x16x32_bf16 v[116:119], v[160:163], v[184:187], v[116:119]
	v_mfma_f32_16x16x32_bf16 v[112:115], v[168:171], v[184:187], v[112:115]
	v_mfma_f32_16x16x32_bf16 v[100:103], v[160:163], v[192:195], v[100:103]
	v_mfma_f32_16x16x32_bf16 v[96:99], v[168:171], v[192:195], v[96:99]
	v_mfma_f32_16x16x32_bf16 v[84:87], v[160:163], v[200:203], v[84:87]
	v_mfma_f32_16x16x32_bf16 v[80:83], v[168:171], v[200:203], v[80:83]
	v_mfma_f32_16x16x32_bf16 v[68:71], v[160:163], v[208:211], v[68:71]
	v_mfma_f32_16x16x32_bf16 v[64:67], v[168:171], v[208:211], v[64:67]
	s_setprio 0
	s_barrier
	s_add_i32 s50, s81, s89
	s_mov_b32 m0, s50
	ds_read_b128 v[172:175], v183 offset:49152
	ds_read_b128 v[184:187], v183 offset:50176
	ds_read_b128 v[188:191], v183 offset:51200
	ds_read_b128 v[192:195], v183 offset:52224
	ds_read_b128 v[196:199], v183 offset:53248
	ds_read_b128 v[200:203], v183 offset:54272
	ds_read_b128 v[204:207], v183 offset:55296
	ds_read_b128 v[208:211], v183 offset:56320
	global_load_lds_dwordx4 v128, s[98:99]
	s_add_i32 m0, s50, 0x2000
	s_add_u32 s50, s68, 0x160080
	s_addc_u32 s51, s69, 0
	s_add_i32 s68, s82, s89
	global_load_lds_dwordx4 v130, s[98:99]
	s_mov_b32 m0, s68
	s_nop 0
	global_load_lds_dwordx4 v128, s[50:51]
	s_add_i32 m0, s68, 0x2000
	s_nop 0
	global_load_lds_dwordx4 v130, s[50:51]
	s_mov_b32 m0, s57
	s_nop 0
	global_load_lds_dwordx4 v128, s[100:101]
	s_mov_b32 m0, s58
	s_nop 0
	global_load_lds_dwordx4 v130, s[100:101]
	s_waitcnt vmcnt(8)
	s_waitcnt lgkmcnt(0)
	s_barrier
	s_setprio 3
	s_waitcnt lgkmcnt(0)
	v_mfma_f32_16x16x32_bf16 v[60:63], v[140:143], v[172:175], v[60:63]
	v_mfma_f32_16x16x32_bf16 v[56:59], v[148:151], v[172:175], v[56:59]
	v_mfma_f32_16x16x32_bf16 v[44:47], v[140:143], v[188:191], v[44:47]
	v_mfma_f32_16x16x32_bf16 v[40:43], v[148:151], v[188:191], v[40:43]
	v_mfma_f32_16x16x32_bf16 v[28:31], v[140:143], v[196:199], v[28:31]
	v_mfma_f32_16x16x32_bf16 v[24:27], v[148:151], v[196:199], v[24:27]
	v_mfma_f32_16x16x32_bf16 v[12:15], v[140:143], v[204:207], v[12:15]
	v_mfma_f32_16x16x32_bf16 v[8:11], v[148:151], v[204:207], v[8:11]
	v_mfma_f32_16x16x32_bf16 v[60:63], v[144:147], v[184:187], v[60:63]
	v_mfma_f32_16x16x32_bf16 v[56:59], v[152:155], v[184:187], v[56:59]
	v_mfma_f32_16x16x32_bf16 v[44:47], v[144:147], v[192:195], v[44:47]
	v_mfma_f32_16x16x32_bf16 v[40:43], v[152:155], v[192:195], v[40:43]
	v_mfma_f32_16x16x32_bf16 v[28:31], v[144:147], v[200:203], v[28:31]
	v_mfma_f32_16x16x32_bf16 v[24:27], v[152:155], v[200:203], v[24:27]
	v_mfma_f32_16x16x32_bf16 v[12:15], v[144:147], v[208:211], v[12:15]
	v_mfma_f32_16x16x32_bf16 v[8:11], v[152:155], v[208:211], v[8:11]
	s_setprio 0
	s_setprio 3
	v_mfma_f32_16x16x32_bf16 v[52:55], v[156:159], v[172:175], v[52:55]
	v_mfma_f32_16x16x32_bf16 v[48:51], v[164:167], v[172:175], v[48:51]
	v_mfma_f32_16x16x32_bf16 v[36:39], v[156:159], v[188:191], v[36:39]
	v_mfma_f32_16x16x32_bf16 v[32:35], v[164:167], v[188:191], v[32:35]
	v_mfma_f32_16x16x32_bf16 v[20:23], v[156:159], v[196:199], v[20:23]
	v_mfma_f32_16x16x32_bf16 v[16:19], v[164:167], v[196:199], v[16:19]
	v_mfma_f32_16x16x32_bf16 v[4:7], v[156:159], v[204:207], v[4:7]
	v_mfma_f32_16x16x32_bf16 v[0:3], v[164:167], v[204:207], v[0:3]
	v_mfma_f32_16x16x32_bf16 v[52:55], v[160:163], v[184:187], v[52:55]
	v_mfma_f32_16x16x32_bf16 v[48:51], v[168:171], v[184:187], v[48:51]
	v_mfma_f32_16x16x32_bf16 v[36:39], v[160:163], v[192:195], v[36:39]
	v_mfma_f32_16x16x32_bf16 v[32:35], v[168:171], v[192:195], v[32:35]
	v_mfma_f32_16x16x32_bf16 v[20:23], v[160:163], v[200:203], v[20:23]
	v_mfma_f32_16x16x32_bf16 v[16:19], v[168:171], v[200:203], v[16:19]
	v_mfma_f32_16x16x32_bf16 v[4:7], v[160:163], v[208:211], v[4:7]
	v_mfma_f32_16x16x32_bf16 v[0:3], v[168:171], v[208:211], v[0:3]
	s_setprio 0
	s_barrier
	s_add_i32 s80, s80, 2
	s_add_u32 s78, s78, 0x100
	s_addc_u32 s79, s79, 0
	s_cmpk_gt_u32 s80, 0x55
	s_mov_b64 s[50:51], s[64:65]
	s_cbranch_scc0 .LBB0_260
	s_and_b64 vcc, exec, s[18:19]
	s_cbranch_vccz .LBB0_263
	s_barrier

.LBB0_347:
	s_ashr_i32 s69, s68, 31
	s_lshl_b64 s[20:21], s[68:69], 20
	s_add_u32 s72, s34, s20
	s_addc_u32 s73, s35, s21
	s_and_b64 s[20:21], s[12:13], exec
	s_cselect_b32 s15, s73, s17
	s_cselect_b32 s29, s72, s16
	s_ashr_i32 s51, s50, 31
	s_lshl_b64 s[20:21], s[50:51], 20
	s_add_u32 s74, s44, s20
	s_addc_u32 s75, s45, s21
	s_and_b64 s[20:21], s[12:13], exec
	s_cselect_b32 s46, s75, s19
	s_cselect_b32 s51, s74, s18
	s_add_u32 s16, s16, 0x80080
	s_addc_u32 s17, s17, 0
	s_add_u32 s69, s18, 0x100
	v_mov_b32_e32 v0, 0
	s_addc_u32 s76, s19, 0
	s_mov_b32 s77, -2
	v_mov_b32_e32 v1, v0
	v_mov_b32_e32 v2, v0
	v_mov_b32_e32 v3, v0
	v_mov_b32_e32 v4, v0
	v_mov_b32_e32 v5, v0
	v_mov_b32_e32 v6, v0
	v_mov_b32_e32 v7, v0
	v_mov_b32_e32 v8, v0
	v_mov_b32_e32 v9, v0
	v_mov_b32_e32 v10, v0
	v_mov_b32_e32 v11, v0
	v_mov_b32_e32 v12, v0
	v_mov_b32_e32 v13, v0
	v_mov_b32_e32 v14, v0
	v_mov_b32_e32 v15, v0
	v_mov_b32_e32 v24, v0
	v_mov_b32_e32 v25, v0
	v_mov_b32_e32 v26, v0
	v_mov_b32_e32 v27, v0
	s_waitcnt vmcnt(0)
	v_mov_b32_e32 v28, v0
	v_mov_b32_e32 v29, v0
	v_mov_b32_e32 v30, v0
	v_mov_b32_e32 v31, v0
	v_mov_b32_e32 v40, v0
	v_mov_b32_e32 v41, v0
	v_mov_b32_e32 v42, v0
	v_mov_b32_e32 v43, v0
	v_mov_b32_e32 v44, v0
	v_mov_b32_e32 v45, v0
	v_mov_b32_e32 v46, v0
	v_mov_b32_e32 v47, v0
	v_mov_b32_e32 v16, v0
	v_mov_b32_e32 v17, v0
	v_mov_b32_e32 v18, v0
	v_mov_b32_e32 v19, v0
	v_mov_b32_e32 v20, v0
	v_mov_b32_e32 v21, v0
	v_mov_b32_e32 v22, v0
	v_mov_b32_e32 v23, v0
	v_mov_b32_e32 v32, v0
	v_mov_b32_e32 v33, v0
	v_mov_b32_e32 v34, v0
	v_mov_b32_e32 v35, v0
	v_mov_b32_e32 v36, v0
	v_mov_b32_e32 v37, v0
	v_mov_b32_e32 v38, v0
	v_mov_b32_e32 v39, v0
	v_mov_b32_e32 v48, v0
	v_mov_b32_e32 v49, v0
	v_mov_b32_e32 v50, v0
	v_mov_b32_e32 v51, v0
	v_mov_b32_e32 v52, v0
	v_mov_b32_e32 v53, v0
	v_mov_b32_e32 v54, v0
	v_mov_b32_e32 v55, v0
	v_mov_b32_e32 v56, v0
	v_mov_b32_e32 v57, v0
	v_mov_b32_e32 v58, v0
	v_mov_b32_e32 v59, v0
	v_mov_b32_e32 v60, v0
	v_mov_b32_e32 v61, v0
	v_mov_b32_e32 v62, v0
	v_mov_b32_e32 v63, v0
	v_mov_b32_e32 v64, v0
	v_mov_b32_e32 v65, v0
	v_mov_b32_e32 v66, v0
	v_mov_b32_e32 v67, v0
	v_mov_b32_e32 v68, v0
	v_mov_b32_e32 v69, v0
	v_mov_b32_e32 v70, v0
	v_mov_b32_e32 v71, v0
	v_mov_b32_e32 v72, v0
	v_mov_b32_e32 v73, v0
	v_mov_b32_e32 v74, v0
	v_mov_b32_e32 v75, v0
	v_mov_b32_e32 v76, v0
	v_mov_b32_e32 v77, v0
	v_mov_b32_e32 v78, v0
	v_mov_b32_e32 v79, v0
	v_mov_b32_e32 v88, v0
	v_mov_b32_e32 v89, v0
	v_mov_b32_e32 v90, v0
	v_mov_b32_e32 v91, v0
	v_mov_b32_e32 v92, v0
	v_mov_b32_e32 v93, v0
	v_mov_b32_e32 v94, v0
	v_mov_b32_e32 v95, v0
	v_mov_b32_e32 v104, v0
	v_mov_b32_e32 v105, v0
	v_mov_b32_e32 v106, v0
	v_mov_b32_e32 v107, v0
	v_mov_b32_e32 v108, v0
	v_mov_b32_e32 v109, v0
	v_mov_b32_e32 v110, v0
	v_mov_b32_e32 v111, v0
	v_mov_b32_e32 v80, v0
	v_mov_b32_e32 v81, v0
	v_mov_b32_e32 v82, v0
	v_mov_b32_e32 v83, v0
	v_mov_b32_e32 v84, v0
	v_mov_b32_e32 v85, v0
	v_mov_b32_e32 v86, v0
	v_mov_b32_e32 v87, v0
	v_mov_b32_e32 v96, v0
	v_mov_b32_e32 v97, v0
	v_mov_b32_e32 v98, v0
	v_mov_b32_e32 v99, v0
	v_mov_b32_e32 v100, v0
	v_mov_b32_e32 v101, v0
	v_mov_b32_e32 v102, v0
	v_mov_b32_e32 v103, v0
	v_mov_b32_e32 v112, v0
	v_mov_b32_e32 v113, v0
	v_mov_b32_e32 v114, v0
	v_mov_b32_e32 v115, v0
	v_mov_b32_e32 v116, v0
	v_mov_b32_e32 v117, v0
	v_mov_b32_e32 v118, v0
	v_mov_b32_e32 v119, v0
	v_mov_b32_e32 v120, v0
	v_mov_b32_e32 v121, v0
	v_mov_b32_e32 v122, v0
	v_mov_b32_e32 v123, v0
	v_mov_b32_e32 v124, v0
	v_mov_b32_e32 v125, v0
	v_mov_b32_e32 v126, v0
	v_mov_b32_e32 v127, v0
	v_add_u32_e32 v206, 0x18000, v242
	v_add_u32_e32 v207, 0x1c000, v242
.LBB0_348:
	ds_read_b128 v[128:131], v243
	ds_read_b128 v[132:135], v243 offset:1024
	ds_read_b128 v[136:139], v243 offset:2048
	ds_read_b128 v[140:143], v243 offset:3072
	ds_read_b128 v[158:161], v244
	ds_read_b128 v[162:165], v244 offset:1024
	ds_read_b128 v[166:169], v244 offset:2048
	ds_read_b128 v[170:173], v244 offset:3072
	s_add_u32 s18, s16, 0xfff80080
	s_addc_u32 s19, s17, -1
	s_cmp_eq_u32 s77, 28
	s_cselect_b32 s21, s15, s19
	s_cselect_b32 s20, s29, s18
	s_cselect_b32 s19, s46, s76
	s_cselect_b32 s18, s51, s69
	s_add_i32 m0, s63, 0xc000
	ds_read_b128 v[174:177], v245
	ds_read_b128 v[178:181], v245 offset:1024
	ds_read_b128 v[182:185], v245 offset:2048
	ds_read_b128 v[186:189], v245 offset:3072
	ds_read_b128 v[190:193], v245 offset:4096
	ds_read_b128 v[194:197], v245 offset:5120
	ds_read_b128 v[198:201], v245 offset:6144
	ds_read_b128 v[202:205], v245 offset:7168
	global_load_lds_dwordx4 v150, s[16:17]
	s_add_i32 m0, s63, 0xe000
	s_nop 0
	global_load_lds_dwordx4 v152, s[16:17]
	s_waitcnt vmcnt(8)
	s_waitcnt lgkmcnt(0)
	s_barrier
	s_setprio 3
	s_waitcnt lgkmcnt(0)
	v_mfma_f32_16x16x32_bf16 v[124:127], v[128:131], v[174:177], v[124:127]
	v_mfma_f32_16x16x32_bf16 v[120:123], v[136:139], v[174:177], v[120:123]
	v_mfma_f32_16x16x32_bf16 v[116:119], v[128:131], v[182:185], v[116:119]
	v_mfma_f32_16x16x32_bf16 v[112:115], v[136:139], v[182:185], v[112:115]
	v_mfma_f32_16x16x32_bf16 v[100:103], v[128:131], v[190:193], v[100:103]
	v_mfma_f32_16x16x32_bf16 v[96:99], v[136:139], v[190:193], v[96:99]
	v_mfma_f32_16x16x32_bf16 v[84:87], v[128:131], v[198:201], v[84:87]
	v_mfma_f32_16x16x32_bf16 v[80:83], v[136:139], v[198:201], v[80:83]
	v_mfma_f32_16x16x32_bf16 v[124:127], v[132:135], v[178:181], v[124:127]
	v_mfma_f32_16x16x32_bf16 v[120:123], v[140:143], v[178:181], v[120:123]
	v_mfma_f32_16x16x32_bf16 v[116:119], v[132:135], v[186:189], v[116:119]
	v_mfma_f32_16x16x32_bf16 v[112:115], v[140:143], v[186:189], v[112:115]
	v_mfma_f32_16x16x32_bf16 v[100:103], v[132:135], v[194:197], v[100:103]
	v_mfma_f32_16x16x32_bf16 v[96:99], v[140:143], v[194:197], v[96:99]
	v_mfma_f32_16x16x32_bf16 v[84:87], v[132:135], v[202:205], v[84:87]
	v_mfma_f32_16x16x32_bf16 v[80:83], v[140:143], v[202:205], v[80:83]
	s_setprio 0
	s_setprio 3
	v_mfma_f32_16x16x32_bf16 v[108:111], v[158:161], v[174:177], v[108:111]
	v_mfma_f32_16x16x32_bf16 v[104:107], v[166:169], v[174:177], v[104:107]
	v_mfma_f32_16x16x32_bf16 v[92:95], v[158:161], v[182:185], v[92:95]
	v_mfma_f32_16x16x32_bf16 v[88:91], v[166:169], v[182:185], v[88:91]
	v_mfma_f32_16x16x32_bf16 v[76:79], v[158:161], v[190:193], v[76:79]
	v_mfma_f32_16x16x32_bf16 v[72:75], v[166:169], v[190:193], v[72:75]
	v_mfma_f32_16x16x32_bf16 v[68:71], v[158:161], v[198:201], v[68:71]
	v_mfma_f32_16x16x32_bf16 v[64:67], v[166:169], v[198:201], v[64:67]
	v_mfma_f32_16x16x32_bf16 v[108:111], v[162:165], v[178:181], v[108:111]
	v_mfma_f32_16x16x32_bf16 v[104:107], v[170:173], v[178:181], v[104:107]
	v_mfma_f32_16x16x32_bf16 v[92:95], v[162:165], v[186:189], v[92:95]
	v_mfma_f32_16x16x32_bf16 v[88:91], v[170:173], v[186:189], v[88:91]
	v_mfma_f32_16x16x32_bf16 v[76:79], v[162:165], v[194:197], v[76:79]
	v_mfma_f32_16x16x32_bf16 v[72:75], v[170:173], v[194:197], v[72:75]
	v_mfma_f32_16x16x32_bf16 v[68:71], v[162:165], v[202:205], v[68:71]
	v_mfma_f32_16x16x32_bf16 v[64:67], v[170:173], v[202:205], v[64:67]
	s_setprio 0
	s_barrier
	s_add_u32 s98, s18, s48
	s_addc_u32 s99, s19, s49
	s_add_u32 s100, s20, s48
	s_addc_u32 s101, s21, s49
	s_add_i32 s78, s93, s89
	s_mov_b32 m0, s78
	ds_read_b128 v[174:177], v245 offset:16384
	ds_read_b128 v[178:181], v245 offset:17408
	ds_read_b128 v[182:185], v245 offset:18432
	ds_read_b128 v[186:189], v245 offset:19456
	ds_read_b128 v[190:193], v245 offset:20480
	ds_read_b128 v[194:197], v245 offset:21504
	ds_read_b128 v[198:201], v245 offset:22528
	ds_read_b128 v[202:205], v245 offset:23552
	global_load_lds_dwordx4 v144, s[18:19]
	s_add_i32 m0, s78, 0x2000
	s_add_u32 s78, s18, 0x80000
	s_addc_u32 s79, s19, 0
	s_add_i32 vcc_lo, s91, s89
	global_load_lds_dwordx4 v146, s[18:19]
	s_mov_b32 m0, vcc_lo
	s_nop 0
	global_load_lds_dwordx4 v144, s[78:79]
	s_add_i32 m0, vcc_lo, 0x2000
	s_nop 0
	global_load_lds_dwordx4 v146, s[78:79]
	s_mov_b32 m0, s63
	s_nop 0
	global_load_lds_dwordx4 v144, s[20:21]
	s_mov_b32 m0, s71
	s_nop 0
	global_load_lds_dwordx4 v146, s[20:21]
	s_waitcnt vmcnt(8)
	s_waitcnt lgkmcnt(0)
	s_barrier
	s_setprio 3
	s_waitcnt lgkmcnt(0)
	v_mfma_f32_16x16x32_bf16 v[60:63], v[128:131], v[174:177], v[60:63]
	v_mfma_f32_16x16x32_bf16 v[56:59], v[136:139], v[174:177], v[56:59]
	v_mfma_f32_16x16x32_bf16 v[52:55], v[128:131], v[182:185], v[52:55]
	v_mfma_f32_16x16x32_bf16 v[48:51], v[136:139], v[182:185], v[48:51]
	v_mfma_f32_16x16x32_bf16 v[36:39], v[128:131], v[190:193], v[36:39]
	v_mfma_f32_16x16x32_bf16 v[32:35], v[136:139], v[190:193], v[32:35]
	v_mfma_f32_16x16x32_bf16 v[20:23], v[128:131], v[198:201], v[20:23]
	v_mfma_f32_16x16x32_bf16 v[16:19], v[136:139], v[198:201], v[16:19]
	v_mfma_f32_16x16x32_bf16 v[60:63], v[132:135], v[178:181], v[60:63]
	v_mfma_f32_16x16x32_bf16 v[56:59], v[140:143], v[178:181], v[56:59]
	v_mfma_f32_16x16x32_bf16 v[52:55], v[132:135], v[186:189], v[52:55]
	v_mfma_f32_16x16x32_bf16 v[48:51], v[140:143], v[186:189], v[48:51]
	v_mfma_f32_16x16x32_bf16 v[36:39], v[132:135], v[194:197], v[36:39]
	v_mfma_f32_16x16x32_bf16 v[32:35], v[140:143], v[194:197], v[32:35]
	v_mfma_f32_16x16x32_bf16 v[20:23], v[132:135], v[202:205], v[20:23]
	v_mfma_f32_16x16x32_bf16 v[16:19], v[140:143], v[202:205], v[16:19]
	s_setprio 0
	s_setprio 3
	v_mfma_f32_16x16x32_bf16 v[44:47], v[158:161], v[174:177], v[44:47]
	v_mfma_f32_16x16x32_bf16 v[40:43], v[166:169], v[174:177], v[40:43]
	v_mfma_f32_16x16x32_bf16 v[28:31], v[158:161], v[182:185], v[28:31]
	v_mfma_f32_16x16x32_bf16 v[24:27], v[166:169], v[182:185], v[24:27]
	v_mfma_f32_16x16x32_bf16 v[12:15], v[158:161], v[190:193], v[12:15]
	v_mfma_f32_16x16x32_bf16 v[8:11], v[166:169], v[190:193], v[8:11]
	v_mfma_f32_16x16x32_bf16 v[4:7], v[158:161], v[198:201], v[4:7]
	v_mfma_f32_16x16x32_bf16 v[0:3], v[166:169], v[198:201], v[0:3]
	v_mfma_f32_16x16x32_bf16 v[44:47], v[162:165], v[178:181], v[44:47]
	v_mfma_f32_16x16x32_bf16 v[40:43], v[170:173], v[178:181], v[40:43]
	v_mfma_f32_16x16x32_bf16 v[28:31], v[162:165], v[186:189], v[28:31]
	v_mfma_f32_16x16x32_bf16 v[24:27], v[170:173], v[186:189], v[24:27]
	v_mfma_f32_16x16x32_bf16 v[12:15], v[162:165], v[194:197], v[12:15]
	v_mfma_f32_16x16x32_bf16 v[8:11], v[170:173], v[194:197], v[8:11]
	v_mfma_f32_16x16x32_bf16 v[4:7], v[162:165], v[202:205], v[4:7]
	v_mfma_f32_16x16x32_bf16 v[0:3], v[170:173], v[202:205], v[0:3]
	s_setprio 0
	s_barrier
	s_add_i32 s78, 0, 0x18000
	s_add_i32 s79, 0, 0x1c000
	ds_read_b128 v[128:131], v206
	ds_read_b128 v[132:135], v206 offset:1024
	ds_read_b128 v[136:139], v206 offset:2048
	ds_read_b128 v[140:143], v206 offset:3072
	ds_read_b128 v[158:161], v207
	ds_read_b128 v[162:165], v207 offset:1024
	ds_read_b128 v[166:169], v207 offset:2048
	ds_read_b128 v[170:173], v207 offset:3072
	s_add_u32 s20, s20, 0x80000
	s_addc_u32 s21, s21, 0
	s_mov_b32 m0, s80
	ds_read_b128 v[174:177], v245 offset:32768
	ds_read_b128 v[178:181], v245 offset:33792
	ds_read_b128 v[182:185], v245 offset:34816
	ds_read_b128 v[186:189], v245 offset:35840
	ds_read_b128 v[190:193], v245 offset:36864
	ds_read_b128 v[194:197], v245 offset:37888
	ds_read_b128 v[198:201], v245 offset:38912
	ds_read_b128 v[202:205], v245 offset:39936
	global_load_lds_dwordx4 v144, s[20:21]
	s_mov_b32 m0, s81
	s_nop 0
	global_load_lds_dwordx4 v146, s[20:21]
	s_waitcnt vmcnt(8)
	s_waitcnt lgkmcnt(0)
	s_barrier
	s_setprio 3
	s_waitcnt lgkmcnt(0)
	v_mfma_f32_16x16x32_bf16 v[124:127], v[128:131], v[174:177], v[124:127]
	v_mfma_f32_16x16x32_bf16 v[120:123], v[136:139], v[174:177], v[120:123]
	v_mfma_f32_16x16x32_bf16 v[116:119], v[128:131], v[182:185], v[116:119]
	v_mfma_f32_16x16x32_bf16 v[112:115], v[136:139], v[182:185], v[112:115]
	v_mfma_f32_16x16x32_bf16 v[100:103], v[128:131], v[190:193], v[100:103]
	v_mfma_f32_16x16x32_bf16 v[96:99], v[136:139], v[190:193], v[96:99]
	v_mfma_f32_16x16x32_bf16 v[84:87], v[128:131], v[198:201], v[84:87]
	v_mfma_f32_16x16x32_bf16 v[80:83], v[136:139], v[198:201], v[80:83]
	v_mfma_f32_16x16x32_bf16 v[124:127], v[132:135], v[178:181], v[124:127]
	v_mfma_f32_16x16x32_bf16 v[120:123], v[140:143], v[178:181], v[120:123]
	v_mfma_f32_16x16x32_bf16 v[116:119], v[132:135], v[186:189], v[116:119]
	v_mfma_f32_16x16x32_bf16 v[112:115], v[140:143], v[186:189], v[112:115]
	v_mfma_f32_16x16x32_bf16 v[100:103], v[132:135], v[194:197], v[100:103]
	v_mfma_f32_16x16x32_bf16 v[96:99], v[140:143], v[194:197], v[96:99]
	v_mfma_f32_16x16x32_bf16 v[84:87], v[132:135], v[202:205], v[84:87]
	v_mfma_f32_16x16x32_bf16 v[80:83], v[140:143], v[202:205], v[80:83]
	s_setprio 0
	s_setprio 3
	v_mfma_f32_16x16x32_bf16 v[108:111], v[158:161], v[174:177], v[108:111]
	v_mfma_f32_16x16x32_bf16 v[104:107], v[166:169], v[174:177], v[104:107]
	v_mfma_f32_16x16x32_bf16 v[92:95], v[158:161], v[182:185], v[92:95]
	v_mfma_f32_16x16x32_bf16 v[88:91], v[166:169], v[182:185], v[88:91]
	v_mfma_f32_16x16x32_bf16 v[76:79], v[158:161], v[190:193], v[76:79]
	v_mfma_f32_16x16x32_bf16 v[72:75], v[166:169], v[190:193], v[72:75]
	v_mfma_f32_16x16x32_bf16 v[68:71], v[158:161], v[198:201], v[68:71]
	v_mfma_f32_16x16x32_bf16 v[64:67], v[166:169], v[198:201], v[64:67]
	v_mfma_f32_16x16x32_bf16 v[108:111], v[162:165], v[178:181], v[108:111]
	v_mfma_f32_16x16x32_bf16 v[104:107], v[170:173], v[178:181], v[104:107]
	v_mfma_f32_16x16x32_bf16 v[92:95], v[162:165], v[186:189], v[92:95]
	v_mfma_f32_16x16x32_bf16 v[88:91], v[170:173], v[186:189], v[88:91]
	v_mfma_f32_16x16x32_bf16 v[76:79], v[162:165], v[194:197], v[76:79]
	v_mfma_f32_16x16x32_bf16 v[72:75], v[170:173], v[194:197], v[72:75]
	v_mfma_f32_16x16x32_bf16 v[68:71], v[162:165], v[202:205], v[68:71]
	v_mfma_f32_16x16x32_bf16 v[64:67], v[170:173], v[202:205], v[64:67]
	s_setprio 0
	s_barrier
	s_add_i32 s20, s78, s89
	s_mov_b32 m0, s20
	ds_read_b128 v[174:177], v245 offset:49152
	ds_read_b128 v[178:181], v245 offset:50176
	ds_read_b128 v[182:185], v245 offset:51200
	ds_read_b128 v[186:189], v245 offset:52224
	ds_read_b128 v[190:193], v245 offset:53248
	ds_read_b128 v[194:197], v245 offset:54272
	ds_read_b128 v[198:201], v245 offset:55296
	ds_read_b128 v[202:205], v245 offset:56320
	global_load_lds_dwordx4 v144, s[98:99]
	s_add_i32 m0, s20, 0x2000
	s_add_u32 s18, s18, 0x80080
	s_addc_u32 s19, s19, 0
	s_add_i32 s20, s79, s89
	global_load_lds_dwordx4 v146, s[98:99]
	s_mov_b32 m0, s20
	s_nop 0
	global_load_lds_dwordx4 v144, s[18:19]
	s_add_i32 m0, s20, 0x2000
	s_nop 0
	global_load_lds_dwordx4 v146, s[18:19]
	s_mov_b32 m0, s92
	s_nop 0
	global_load_lds_dwordx4 v144, s[100:101]
	s_mov_b32 m0, s88
	s_nop 0
	global_load_lds_dwordx4 v146, s[100:101]
	s_waitcnt vmcnt(8)
	s_waitcnt lgkmcnt(0)
	s_barrier
	s_setprio 3
	s_waitcnt lgkmcnt(0)
	v_mfma_f32_16x16x32_bf16 v[60:63], v[128:131], v[174:177], v[60:63]
	v_mfma_f32_16x16x32_bf16 v[56:59], v[136:139], v[174:177], v[56:59]
	v_mfma_f32_16x16x32_bf16 v[52:55], v[128:131], v[182:185], v[52:55]
	v_mfma_f32_16x16x32_bf16 v[48:51], v[136:139], v[182:185], v[48:51]
	v_mfma_f32_16x16x32_bf16 v[36:39], v[128:131], v[190:193], v[36:39]
	v_mfma_f32_16x16x32_bf16 v[32:35], v[136:139], v[190:193], v[32:35]
	v_mfma_f32_16x16x32_bf16 v[20:23], v[128:131], v[198:201], v[20:23]
	v_mfma_f32_16x16x32_bf16 v[16:19], v[136:139], v[198:201], v[16:19]
	v_mfma_f32_16x16x32_bf16 v[60:63], v[132:135], v[178:181], v[60:63]
	v_mfma_f32_16x16x32_bf16 v[56:59], v[140:143], v[178:181], v[56:59]
	v_mfma_f32_16x16x32_bf16 v[52:55], v[132:135], v[186:189], v[52:55]
	v_mfma_f32_16x16x32_bf16 v[48:51], v[140:143], v[186:189], v[48:51]
	v_mfma_f32_16x16x32_bf16 v[36:39], v[132:135], v[194:197], v[36:39]
	v_mfma_f32_16x16x32_bf16 v[32:35], v[140:143], v[194:197], v[32:35]
	v_mfma_f32_16x16x32_bf16 v[20:23], v[132:135], v[202:205], v[20:23]
	v_mfma_f32_16x16x32_bf16 v[16:19], v[140:143], v[202:205], v[16:19]
	s_setprio 0
	s_setprio 3
	v_mfma_f32_16x16x32_bf16 v[44:47], v[158:161], v[174:177], v[44:47]
	v_mfma_f32_16x16x32_bf16 v[40:43], v[166:169], v[174:177], v[40:43]
	v_mfma_f32_16x16x32_bf16 v[28:31], v[158:161], v[182:185], v[28:31]
	v_mfma_f32_16x16x32_bf16 v[24:27], v[166:169], v[182:185], v[24:27]
	v_mfma_f32_16x16x32_bf16 v[12:15], v[158:161], v[190:193], v[12:15]
	v_mfma_f32_16x16x32_bf16 v[8:11], v[166:169], v[190:193], v[8:11]
	v_mfma_f32_16x16x32_bf16 v[4:7], v[158:161], v[198:201], v[4:7]
	v_mfma_f32_16x16x32_bf16 v[0:3], v[166:169], v[198:201], v[0:3]
	v_mfma_f32_16x16x32_bf16 v[44:47], v[162:165], v[178:181], v[44:47]
	v_mfma_f32_16x16x32_bf16 v[40:43], v[170:173], v[178:181], v[40:43]
	v_mfma_f32_16x16x32_bf16 v[28:31], v[162:165], v[186:189], v[28:31]
	v_mfma_f32_16x16x32_bf16 v[24:27], v[170:173], v[186:189], v[24:27]
	v_mfma_f32_16x16x32_bf16 v[12:15], v[162:165], v[194:197], v[12:15]
	v_mfma_f32_16x16x32_bf16 v[8:11], v[170:173], v[194:197], v[8:11]
	v_mfma_f32_16x16x32_bf16 v[4:7], v[162:165], v[202:205], v[4:7]
	v_mfma_f32_16x16x32_bf16 v[0:3], v[170:173], v[202:205], v[0:3]
	s_setprio 0
	s_barrier
	s_add_i32 s77, s77, 2
	s_add_u32 s16, s16, 0x100
	s_addc_u32 s17, s17, 0
	s_add_u32 s69, s69, 0x100
	s_addc_u32 s76, s76, 0
	s_cmp_gt_u32 s77, 29
	s_cbranch_scc0 .LBB0_348
	s_and_b64 vcc, exec, s[64:65]
	s_cbranch_vccz .LBB0_351
	s_barrier

.LBB0_749:
	s_ashr_i32 s21, s20, 31
	s_lshl_b64 s[36:37], s[20:21], 20
	s_add_u32 s36, s14, s36
	s_addc_u32 s37, s15, s37
	s_and_b64 s[38:39], s[10:11], exec
	s_cselect_b32 s21, s37, s45
	s_cselect_b32 s41, s36, s44
	s_ashr_i32 s19, s18, 31
	s_lshl_b64 s[38:39], s[18:19], 20
	s_add_u32 s38, s66, s38
	s_addc_u32 s39, s67, s39
	s_and_b64 s[48:49], s[10:11], exec
	s_cselect_b32 s19, s39, s47
	s_cselect_b32 s60, s38, s46
	s_add_u32 s61, s46, 0x100
	v_mov_b32_e32 v0, 0
	s_addc_u32 s62, s47, 0
	s_mov_b32 s63, -2
	s_waitcnt lgkmcnt(0)
	v_mov_b32_e32 v1, v0
	v_mov_b32_e32 v2, v0
	v_mov_b32_e32 v3, v0
	v_mov_b32_e32 v4, v0
	v_mov_b32_e32 v5, v0
	v_mov_b32_e32 v6, v0
	v_mov_b32_e32 v7, v0
	v_mov_b32_e32 v16, v0
	v_mov_b32_e32 v17, v0
	v_mov_b32_e32 v18, v0
	v_mov_b32_e32 v19, v0
	v_mov_b32_e32 v20, v0
	v_mov_b32_e32 v21, v0
	v_mov_b32_e32 v22, v0
	v_mov_b32_e32 v23, v0
	v_mov_b32_e32 v32, v0
	v_mov_b32_e32 v33, v0
	v_mov_b32_e32 v34, v0
	v_mov_b32_e32 v35, v0
	v_mov_b32_e32 v36, v0
	v_mov_b32_e32 v37, v0
	v_mov_b32_e32 v38, v0
	v_mov_b32_e32 v39, v0
	v_mov_b32_e32 v48, v0
	v_mov_b32_e32 v49, v0
	v_mov_b32_e32 v50, v0
	v_mov_b32_e32 v51, v0
	v_mov_b32_e32 v52, v0
	v_mov_b32_e32 v53, v0
	v_mov_b32_e32 v54, v0
	v_mov_b32_e32 v55, v0
	v_mov_b32_e32 v8, v0
	v_mov_b32_e32 v9, v0
	v_mov_b32_e32 v10, v0
	v_mov_b32_e32 v11, v0
	v_mov_b32_e32 v12, v0
	v_mov_b32_e32 v13, v0
	v_mov_b32_e32 v14, v0
	v_mov_b32_e32 v15, v0
	v_mov_b32_e32 v24, v0
	v_mov_b32_e32 v25, v0
	v_mov_b32_e32 v26, v0
	v_mov_b32_e32 v27, v0
	v_mov_b32_e32 v28, v0
	v_mov_b32_e32 v29, v0
	v_mov_b32_e32 v30, v0
	v_mov_b32_e32 v31, v0
	v_mov_b32_e32 v40, v0
	v_mov_b32_e32 v41, v0
	v_mov_b32_e32 v42, v0
	v_mov_b32_e32 v43, v0
	v_mov_b32_e32 v44, v0
	v_mov_b32_e32 v45, v0
	v_mov_b32_e32 v46, v0
	v_mov_b32_e32 v47, v0
	v_mov_b32_e32 v56, v0
	v_mov_b32_e32 v57, v0
	v_mov_b32_e32 v58, v0
	v_mov_b32_e32 v59, v0
	v_mov_b32_e32 v60, v0
	v_mov_b32_e32 v61, v0
	v_mov_b32_e32 v62, v0
	v_mov_b32_e32 v63, v0
	v_mov_b32_e32 v64, v0
	v_mov_b32_e32 v65, v0
	v_mov_b32_e32 v66, v0
	v_mov_b32_e32 v67, v0
	v_mov_b32_e32 v68, v0
	v_mov_b32_e32 v69, v0
	v_mov_b32_e32 v70, v0
	v_mov_b32_e32 v71, v0
	v_mov_b32_e32 v80, v0
	v_mov_b32_e32 v81, v0
	v_mov_b32_e32 v82, v0
	v_mov_b32_e32 v83, v0
	v_mov_b32_e32 v84, v0
	v_mov_b32_e32 v85, v0
	v_mov_b32_e32 v86, v0
	v_mov_b32_e32 v87, v0
	v_mov_b32_e32 v96, v0
	v_mov_b32_e32 v97, v0
	v_mov_b32_e32 v98, v0
	v_mov_b32_e32 v99, v0
	v_mov_b32_e32 v100, v0
	v_mov_b32_e32 v101, v0
	v_mov_b32_e32 v102, v0
	v_mov_b32_e32 v103, v0
	v_mov_b32_e32 v112, v0
	v_mov_b32_e32 v113, v0
	v_mov_b32_e32 v114, v0
	v_mov_b32_e32 v115, v0
	v_mov_b32_e32 v116, v0
	v_mov_b32_e32 v117, v0
	v_mov_b32_e32 v118, v0
	v_mov_b32_e32 v119, v0
	v_mov_b32_e32 v72, v0
	v_mov_b32_e32 v73, v0
	v_mov_b32_e32 v74, v0
	v_mov_b32_e32 v75, v0
	v_mov_b32_e32 v76, v0
	v_mov_b32_e32 v77, v0
	v_mov_b32_e32 v78, v0
	v_mov_b32_e32 v79, v0
	v_mov_b32_e32 v88, v0
	v_mov_b32_e32 v89, v0
	v_mov_b32_e32 v90, v0
	v_mov_b32_e32 v91, v0
	v_mov_b32_e32 v92, v0
	v_mov_b32_e32 v93, v0
	v_mov_b32_e32 v94, v0
	v_mov_b32_e32 v95, v0
	v_mov_b32_e32 v104, v0
	v_mov_b32_e32 v105, v0
	v_mov_b32_e32 v106, v0
	v_mov_b32_e32 v107, v0
	v_mov_b32_e32 v108, v0
	v_mov_b32_e32 v109, v0
	v_mov_b32_e32 v110, v0
	v_mov_b32_e32 v111, v0
	v_mov_b32_e32 v120, v0
	v_mov_b32_e32 v121, v0
	v_mov_b32_e32 v122, v0
	v_mov_b32_e32 v123, v0
	v_mov_b32_e32 v124, v0
	v_mov_b32_e32 v125, v0
	v_mov_b32_e32 v126, v0
	v_mov_b32_e32 v127, v0
	v_add_u32_e32 v180, 0x18000, v183
	v_add_u32_e32 v181, 0x1c000, v183
.LBB0_750:
	ds_read_b128 v[140:143], v187
	ds_read_b128 v[144:147], v187 offset:1024
	ds_read_b128 v[148:151], v187 offset:2048
	ds_read_b128 v[152:155], v187 offset:3072
	ds_read_b128 v[156:159], v188
	ds_read_b128 v[160:163], v188 offset:1024
	ds_read_b128 v[164:167], v188 offset:2048
	ds_read_b128 v[168:171], v188 offset:3072
	s_add_u32 s46, s44, 0x100
	s_addc_u32 s47, s45, 0
	s_cmp_eq_u32 s63, 28
	s_cselect_b32 s51, s21, s47
	s_cselect_b32 s50, s41, s46
	s_cselect_b32 s49, s19, s62
	s_cselect_b32 s48, s60, s61
	s_add_i32 m0, s4, 0xc000
	ds_read_b128 v[172:175], v189
	ds_read_b128 v[176:179], v189 offset:1024
	ds_read_b128 v[190:193], v189 offset:2048
	ds_read_b128 v[194:197], v189 offset:3072
	ds_read_b128 v[198:201], v189 offset:4096
	ds_read_b128 v[202:205], v189 offset:5120
	ds_read_b128 v[206:209], v189 offset:6144
	ds_read_b128 v[210:213], v189 offset:7168
	global_load_lds_dwordx4 v132, s[44:45]
	s_add_i32 m0, s4, 0xe000
	s_nop 0
	global_load_lds_dwordx4 v134, s[44:45]
	s_waitcnt vmcnt(8)
	s_waitcnt lgkmcnt(0)
	s_barrier
	s_setprio 3
	s_waitcnt lgkmcnt(0)
	v_mfma_f32_16x16x32_bf16 v[124:127], v[140:143], v[172:175], v[124:127]
	v_mfma_f32_16x16x32_bf16 v[120:123], v[148:151], v[172:175], v[120:123]
	v_mfma_f32_16x16x32_bf16 v[108:111], v[140:143], v[190:193], v[108:111]
	v_mfma_f32_16x16x32_bf16 v[104:107], v[148:151], v[190:193], v[104:107]
	v_mfma_f32_16x16x32_bf16 v[92:95], v[140:143], v[198:201], v[92:95]
	v_mfma_f32_16x16x32_bf16 v[88:91], v[148:151], v[198:201], v[88:91]
	v_mfma_f32_16x16x32_bf16 v[76:79], v[140:143], v[206:209], v[76:79]
	v_mfma_f32_16x16x32_bf16 v[72:75], v[148:151], v[206:209], v[72:75]
	v_mfma_f32_16x16x32_bf16 v[124:127], v[144:147], v[176:179], v[124:127]
	v_mfma_f32_16x16x32_bf16 v[120:123], v[152:155], v[176:179], v[120:123]
	v_mfma_f32_16x16x32_bf16 v[108:111], v[144:147], v[194:197], v[108:111]
	v_mfma_f32_16x16x32_bf16 v[104:107], v[152:155], v[194:197], v[104:107]
	v_mfma_f32_16x16x32_bf16 v[92:95], v[144:147], v[202:205], v[92:95]
	v_mfma_f32_16x16x32_bf16 v[88:91], v[152:155], v[202:205], v[88:91]
	v_mfma_f32_16x16x32_bf16 v[76:79], v[144:147], v[210:213], v[76:79]
	v_mfma_f32_16x16x32_bf16 v[72:75], v[152:155], v[210:213], v[72:75]
	s_setprio 0
	s_setprio 3
	v_mfma_f32_16x16x32_bf16 v[116:119], v[156:159], v[172:175], v[116:119]
	v_mfma_f32_16x16x32_bf16 v[112:115], v[164:167], v[172:175], v[112:115]
	v_mfma_f32_16x16x32_bf16 v[100:103], v[156:159], v[190:193], v[100:103]
	v_mfma_f32_16x16x32_bf16 v[96:99], v[164:167], v[190:193], v[96:99]
	v_mfma_f32_16x16x32_bf16 v[84:87], v[156:159], v[198:201], v[84:87]
	v_mfma_f32_16x16x32_bf16 v[80:83], v[164:167], v[198:201], v[80:83]
	v_mfma_f32_16x16x32_bf16 v[68:71], v[156:159], v[206:209], v[68:71]
	v_mfma_f32_16x16x32_bf16 v[64:67], v[164:167], v[206:209], v[64:67]
	v_mfma_f32_16x16x32_bf16 v[116:119], v[160:163], v[176:179], v[116:119]
	v_mfma_f32_16x16x32_bf16 v[112:115], v[168:171], v[176:179], v[112:115]
	v_mfma_f32_16x16x32_bf16 v[100:103], v[160:163], v[194:197], v[100:103]
	v_mfma_f32_16x16x32_bf16 v[96:99], v[168:171], v[194:197], v[96:99]
	v_mfma_f32_16x16x32_bf16 v[84:87], v[160:163], v[202:205], v[84:87]
	v_mfma_f32_16x16x32_bf16 v[80:83], v[168:171], v[202:205], v[80:83]
	v_mfma_f32_16x16x32_bf16 v[68:71], v[160:163], v[210:213], v[68:71]
	v_mfma_f32_16x16x32_bf16 v[64:67], v[168:171], v[210:213], v[64:67]
	s_setprio 0
	s_barrier
	s_add_u32 s98, s48, s16
	s_addc_u32 s99, s49, s17
	s_add_u32 s100, s50, s16
	s_addc_u32 s101, s51, s17
	s_add_i32 s44, s58, s89
	s_mov_b32 m0, s44
	ds_read_b128 v[172:175], v189 offset:16384
	ds_read_b128 v[176:179], v189 offset:17408
	ds_read_b128 v[190:193], v189 offset:18432
	ds_read_b128 v[194:197], v189 offset:19456
	ds_read_b128 v[198:201], v189 offset:20480
	ds_read_b128 v[202:205], v189 offset:21504
	ds_read_b128 v[206:209], v189 offset:22528
	ds_read_b128 v[210:213], v189 offset:23552
	global_load_lds_dwordx4 v128, s[48:49]
	s_add_i32 m0, s44, 0x2000
	s_add_u32 s44, s48, 0x80000
	s_addc_u32 s45, s49, 0
	s_add_i32 s68, s59, s89
	global_load_lds_dwordx4 v130, s[48:49]
	s_mov_b32 m0, s68
	s_nop 0
	global_load_lds_dwordx4 v128, s[44:45]
	s_add_i32 m0, s68, 0x2000
	s_nop 0
	global_load_lds_dwordx4 v130, s[44:45]
	s_mov_b32 m0, s4
	s_nop 0
	global_load_lds_dwordx4 v128, s[50:51]
	s_mov_b32 m0, s5
	s_nop 0
	global_load_lds_dwordx4 v130, s[50:51]
	s_waitcnt vmcnt(8)
	s_waitcnt lgkmcnt(0)
	s_barrier
	s_setprio 3
	s_waitcnt lgkmcnt(0)
	v_mfma_f32_16x16x32_bf16 v[60:63], v[140:143], v[172:175], v[60:63]
	v_mfma_f32_16x16x32_bf16 v[56:59], v[148:151], v[172:175], v[56:59]
	v_mfma_f32_16x16x32_bf16 v[44:47], v[140:143], v[190:193], v[44:47]
	v_mfma_f32_16x16x32_bf16 v[40:43], v[148:151], v[190:193], v[40:43]
	v_mfma_f32_16x16x32_bf16 v[28:31], v[140:143], v[198:201], v[28:31]
	v_mfma_f32_16x16x32_bf16 v[24:27], v[148:151], v[198:201], v[24:27]
	v_mfma_f32_16x16x32_bf16 v[12:15], v[140:143], v[206:209], v[12:15]
	v_mfma_f32_16x16x32_bf16 v[8:11], v[148:151], v[206:209], v[8:11]
	v_mfma_f32_16x16x32_bf16 v[60:63], v[144:147], v[176:179], v[60:63]
	v_mfma_f32_16x16x32_bf16 v[56:59], v[152:155], v[176:179], v[56:59]
	v_mfma_f32_16x16x32_bf16 v[44:47], v[144:147], v[194:197], v[44:47]
	v_mfma_f32_16x16x32_bf16 v[40:43], v[152:155], v[194:197], v[40:43]
	v_mfma_f32_16x16x32_bf16 v[28:31], v[144:147], v[202:205], v[28:31]
	v_mfma_f32_16x16x32_bf16 v[24:27], v[152:155], v[202:205], v[24:27]
	v_mfma_f32_16x16x32_bf16 v[12:15], v[144:147], v[210:213], v[12:15]
	v_mfma_f32_16x16x32_bf16 v[8:11], v[152:155], v[210:213], v[8:11]
	s_setprio 0
	s_setprio 3
	v_mfma_f32_16x16x32_bf16 v[52:55], v[156:159], v[172:175], v[52:55]
	v_mfma_f32_16x16x32_bf16 v[48:51], v[164:167], v[172:175], v[48:51]
	v_mfma_f32_16x16x32_bf16 v[36:39], v[156:159], v[190:193], v[36:39]
	v_mfma_f32_16x16x32_bf16 v[32:35], v[164:167], v[190:193], v[32:35]
	v_mfma_f32_16x16x32_bf16 v[20:23], v[156:159], v[198:201], v[20:23]
	v_mfma_f32_16x16x32_bf16 v[16:19], v[164:167], v[198:201], v[16:19]
	v_mfma_f32_16x16x32_bf16 v[4:7], v[156:159], v[206:209], v[4:7]
	v_mfma_f32_16x16x32_bf16 v[0:3], v[164:167], v[206:209], v[0:3]
	v_mfma_f32_16x16x32_bf16 v[52:55], v[160:163], v[176:179], v[52:55]
	v_mfma_f32_16x16x32_bf16 v[48:51], v[168:171], v[176:179], v[48:51]
	v_mfma_f32_16x16x32_bf16 v[36:39], v[160:163], v[194:197], v[36:39]
	v_mfma_f32_16x16x32_bf16 v[32:35], v[168:171], v[194:197], v[32:35]
	v_mfma_f32_16x16x32_bf16 v[20:23], v[160:163], v[202:205], v[20:23]
	v_mfma_f32_16x16x32_bf16 v[16:19], v[168:171], v[202:205], v[16:19]
	v_mfma_f32_16x16x32_bf16 v[4:7], v[160:163], v[210:213], v[4:7]
	v_mfma_f32_16x16x32_bf16 v[0:3], v[168:171], v[210:213], v[0:3]
	s_setprio 0
	s_barrier
	s_add_i32 s68, 0, 0x18000
	s_add_i32 s69, 0, 0x1c000
	ds_read_b128 v[140:143], v180
	ds_read_b128 v[144:147], v180 offset:1024
	ds_read_b128 v[148:151], v180 offset:2048
	ds_read_b128 v[152:155], v180 offset:3072
	ds_read_b128 v[156:159], v181
	ds_read_b128 v[160:163], v181 offset:1024
	ds_read_b128 v[164:167], v181 offset:2048
	ds_read_b128 v[168:171], v181 offset:3072
	s_add_u32 s44, s50, 0x80000
	s_addc_u32 s45, s51, 0
	s_mov_b32 m0, s28
	ds_read_b128 v[172:175], v189 offset:32768
	ds_read_b128 v[176:179], v189 offset:33792
	ds_read_b128 v[190:193], v189 offset:34816
	ds_read_b128 v[194:197], v189 offset:35840
	ds_read_b128 v[198:201], v189 offset:36864
	ds_read_b128 v[202:205], v189 offset:37888
	ds_read_b128 v[206:209], v189 offset:38912
	ds_read_b128 v[210:213], v189 offset:39936
	global_load_lds_dwordx4 v128, s[44:45]
	s_mov_b32 m0, s29
	s_nop 0
	global_load_lds_dwordx4 v130, s[44:45]
	s_waitcnt vmcnt(8)
	s_waitcnt lgkmcnt(0)
	s_barrier
	s_setprio 3
	s_waitcnt lgkmcnt(0)
	v_mfma_f32_16x16x32_bf16 v[124:127], v[140:143], v[172:175], v[124:127]
	v_mfma_f32_16x16x32_bf16 v[120:123], v[148:151], v[172:175], v[120:123]
	v_mfma_f32_16x16x32_bf16 v[108:111], v[140:143], v[190:193], v[108:111]
	v_mfma_f32_16x16x32_bf16 v[104:107], v[148:151], v[190:193], v[104:107]
	v_mfma_f32_16x16x32_bf16 v[92:95], v[140:143], v[198:201], v[92:95]
	v_mfma_f32_16x16x32_bf16 v[88:91], v[148:151], v[198:201], v[88:91]
	v_mfma_f32_16x16x32_bf16 v[76:79], v[140:143], v[206:209], v[76:79]
	v_mfma_f32_16x16x32_bf16 v[72:75], v[148:151], v[206:209], v[72:75]
	v_mfma_f32_16x16x32_bf16 v[124:127], v[144:147], v[176:179], v[124:127]
	v_mfma_f32_16x16x32_bf16 v[120:123], v[152:155], v[176:179], v[120:123]
	v_mfma_f32_16x16x32_bf16 v[108:111], v[144:147], v[194:197], v[108:111]
	v_mfma_f32_16x16x32_bf16 v[104:107], v[152:155], v[194:197], v[104:107]
	v_mfma_f32_16x16x32_bf16 v[92:95], v[144:147], v[202:205], v[92:95]
	v_mfma_f32_16x16x32_bf16 v[88:91], v[152:155], v[202:205], v[88:91]
	v_mfma_f32_16x16x32_bf16 v[76:79], v[144:147], v[210:213], v[76:79]
	v_mfma_f32_16x16x32_bf16 v[72:75], v[152:155], v[210:213], v[72:75]
	s_setprio 0
	s_setprio 3
	v_mfma_f32_16x16x32_bf16 v[116:119], v[156:159], v[172:175], v[116:119]
	v_mfma_f32_16x16x32_bf16 v[112:115], v[164:167], v[172:175], v[112:115]
	v_mfma_f32_16x16x32_bf16 v[100:103], v[156:159], v[190:193], v[100:103]
	v_mfma_f32_16x16x32_bf16 v[96:99], v[164:167], v[190:193], v[96:99]
	v_mfma_f32_16x16x32_bf16 v[84:87], v[156:159], v[198:201], v[84:87]
	v_mfma_f32_16x16x32_bf16 v[80:83], v[164:167], v[198:201], v[80:83]
	v_mfma_f32_16x16x32_bf16 v[68:71], v[156:159], v[206:209], v[68:71]
	v_mfma_f32_16x16x32_bf16 v[64:67], v[164:167], v[206:209], v[64:67]
	v_mfma_f32_16x16x32_bf16 v[116:119], v[160:163], v[176:179], v[116:119]
	v_mfma_f32_16x16x32_bf16 v[112:115], v[168:171], v[176:179], v[112:115]
	v_mfma_f32_16x16x32_bf16 v[100:103], v[160:163], v[194:197], v[100:103]
	v_mfma_f32_16x16x32_bf16 v[96:99], v[168:171], v[194:197], v[96:99]
	v_mfma_f32_16x16x32_bf16 v[84:87], v[160:163], v[202:205], v[84:87]
	v_mfma_f32_16x16x32_bf16 v[80:83], v[168:171], v[202:205], v[80:83]
	v_mfma_f32_16x16x32_bf16 v[68:71], v[160:163], v[210:213], v[68:71]
	v_mfma_f32_16x16x32_bf16 v[64:67], v[168:171], v[210:213], v[64:67]
	s_setprio 0
	s_barrier
	s_add_i32 s44, s68, s89
	s_mov_b32 m0, s44
	ds_read_b128 v[172:175], v189 offset:49152
	ds_read_b128 v[176:179], v189 offset:50176
	ds_read_b128 v[190:193], v189 offset:51200
	ds_read_b128 v[194:197], v189 offset:52224
	ds_read_b128 v[198:201], v189 offset:53248
	ds_read_b128 v[202:205], v189 offset:54272
	ds_read_b128 v[206:209], v189 offset:55296
	ds_read_b128 v[210:213], v189 offset:56320
	global_load_lds_dwordx4 v128, s[98:99]
	s_add_i32 m0, s44, 0x2000
	s_add_u32 s44, s48, 0x80080
	s_addc_u32 s45, s49, 0
	s_add_i32 s48, s69, s89
	global_load_lds_dwordx4 v130, s[98:99]
	s_mov_b32 m0, s48
	s_nop 0
	global_load_lds_dwordx4 v128, s[44:45]
	s_add_i32 m0, s48, 0x2000
	s_nop 0
	global_load_lds_dwordx4 v130, s[44:45]
	s_mov_b32 m0, s56
	s_nop 0
	global_load_lds_dwordx4 v128, s[100:101]
	s_mov_b32 m0, s57
	s_nop 0
	global_load_lds_dwordx4 v130, s[100:101]
	s_waitcnt vmcnt(8)
	s_waitcnt lgkmcnt(0)
	s_barrier
	s_setprio 3
	s_waitcnt lgkmcnt(0)
	v_mfma_f32_16x16x32_bf16 v[60:63], v[140:143], v[172:175], v[60:63]
	v_mfma_f32_16x16x32_bf16 v[56:59], v[148:151], v[172:175], v[56:59]
	v_mfma_f32_16x16x32_bf16 v[44:47], v[140:143], v[190:193], v[44:47]
	v_mfma_f32_16x16x32_bf16 v[40:43], v[148:151], v[190:193], v[40:43]
	v_mfma_f32_16x16x32_bf16 v[28:31], v[140:143], v[198:201], v[28:31]
	v_mfma_f32_16x16x32_bf16 v[24:27], v[148:151], v[198:201], v[24:27]
	v_mfma_f32_16x16x32_bf16 v[12:15], v[140:143], v[206:209], v[12:15]
	v_mfma_f32_16x16x32_bf16 v[8:11], v[148:151], v[206:209], v[8:11]
	v_mfma_f32_16x16x32_bf16 v[60:63], v[144:147], v[176:179], v[60:63]
	v_mfma_f32_16x16x32_bf16 v[56:59], v[152:155], v[176:179], v[56:59]
	v_mfma_f32_16x16x32_bf16 v[44:47], v[144:147], v[194:197], v[44:47]
	v_mfma_f32_16x16x32_bf16 v[40:43], v[152:155], v[194:197], v[40:43]
	v_mfma_f32_16x16x32_bf16 v[28:31], v[144:147], v[202:205], v[28:31]
	v_mfma_f32_16x16x32_bf16 v[24:27], v[152:155], v[202:205], v[24:27]
	v_mfma_f32_16x16x32_bf16 v[12:15], v[144:147], v[210:213], v[12:15]
	v_mfma_f32_16x16x32_bf16 v[8:11], v[152:155], v[210:213], v[8:11]
	s_setprio 0
	s_setprio 3
	v_mfma_f32_16x16x32_bf16 v[52:55], v[156:159], v[172:175], v[52:55]
	v_mfma_f32_16x16x32_bf16 v[48:51], v[164:167], v[172:175], v[48:51]
	v_mfma_f32_16x16x32_bf16 v[36:39], v[156:159], v[190:193], v[36:39]
	v_mfma_f32_16x16x32_bf16 v[32:35], v[164:167], v[190:193], v[32:35]
	v_mfma_f32_16x16x32_bf16 v[20:23], v[156:159], v[198:201], v[20:23]
	v_mfma_f32_16x16x32_bf16 v[16:19], v[164:167], v[198:201], v[16:19]
	v_mfma_f32_16x16x32_bf16 v[4:7], v[156:159], v[206:209], v[4:7]
	v_mfma_f32_16x16x32_bf16 v[0:3], v[164:167], v[206:209], v[0:3]
	v_mfma_f32_16x16x32_bf16 v[52:55], v[160:163], v[176:179], v[52:55]
	v_mfma_f32_16x16x32_bf16 v[48:51], v[168:171], v[176:179], v[48:51]
	v_mfma_f32_16x16x32_bf16 v[36:39], v[160:163], v[194:197], v[36:39]
	v_mfma_f32_16x16x32_bf16 v[32:35], v[168:171], v[194:197], v[32:35]
	v_mfma_f32_16x16x32_bf16 v[20:23], v[160:163], v[202:205], v[20:23]
	v_mfma_f32_16x16x32_bf16 v[16:19], v[168:171], v[202:205], v[16:19]
	v_mfma_f32_16x16x32_bf16 v[4:7], v[160:163], v[210:213], v[4:7]
	v_mfma_f32_16x16x32_bf16 v[0:3], v[168:171], v[210:213], v[0:3]
	s_setprio 0
	s_barrier
	s_add_i32 s63, s63, 2
	s_add_u32 s61, s61, 0x100
	s_addc_u32 s62, s62, 0
	s_cmp_gt_u32 s63, 29
	s_mov_b64 s[44:45], s[46:47]
	s_cbranch_scc0 .LBB0_750
	s_and_b64 vcc, exec, s[64:65]
	s_cbranch_vccz .LBB0_753
	s_barrier

.LBB0_835:
	s_ashr_i32 s17, s16, 31
	s_lshl_b64 s[18:19], s[16:17], 20
	s_add_u32 s18, s34, s18
	s_addc_u32 s19, s35, s19
	s_and_b64 s[20:21], s[8:9], exec
	s_cselect_b32 s17, s19, s39
	s_cselect_b32 s51, s18, s38
	s_ashr_i32 s15, s14, 31
	s_lshl_b64 s[20:21], s[14:15], 20
	s_add_u32 s20, s54, s20
	s_addc_u32 s21, s55, s21
	s_and_b64 s[42:43], s[8:9], exec
	s_cselect_b32 s15, s21, s41
	s_cselect_b32 s56, s20, s40
	s_add_u32 s38, s38, 0x80080
	s_addc_u32 s39, s39, 0
	s_add_u32 s57, s40, 0x100
	v_mov_b32_e32 v0, 0
	s_addc_u32 s58, s41, 0
	s_mov_b32 s59, -2
	v_mov_b32_e32 v1, v0
	v_mov_b32_e32 v2, v0
	v_mov_b32_e32 v3, v0
	v_mov_b32_e32 v4, v0
	v_mov_b32_e32 v5, v0
	v_mov_b32_e32 v6, v0
	v_mov_b32_e32 v7, v0
	v_mov_b32_e32 v16, v0
	v_mov_b32_e32 v17, v0
	v_mov_b32_e32 v18, v0
	v_mov_b32_e32 v19, v0
	v_mov_b32_e32 v20, v0
	v_mov_b32_e32 v21, v0
	v_mov_b32_e32 v22, v0
	v_mov_b32_e32 v23, v0
	v_mov_b32_e32 v32, v0
	v_mov_b32_e32 v33, v0
	v_mov_b32_e32 v34, v0
	v_mov_b32_e32 v35, v0
	v_mov_b32_e32 v36, v0
	v_mov_b32_e32 v37, v0
	v_mov_b32_e32 v38, v0
	v_mov_b32_e32 v39, v0
	v_mov_b32_e32 v48, v0
	v_mov_b32_e32 v49, v0
	v_mov_b32_e32 v50, v0
	v_mov_b32_e32 v51, v0
	v_mov_b32_e32 v52, v0
	v_mov_b32_e32 v53, v0
	v_mov_b32_e32 v54, v0
	v_mov_b32_e32 v55, v0
	v_mov_b32_e32 v8, v0
	v_mov_b32_e32 v9, v0
	v_mov_b32_e32 v10, v0
	v_mov_b32_e32 v11, v0
	v_mov_b32_e32 v12, v0
	v_mov_b32_e32 v13, v0
	v_mov_b32_e32 v14, v0
	v_mov_b32_e32 v15, v0
	v_mov_b32_e32 v24, v0
	v_mov_b32_e32 v25, v0
	v_mov_b32_e32 v26, v0
	v_mov_b32_e32 v27, v0
	v_mov_b32_e32 v28, v0
	v_mov_b32_e32 v29, v0
	v_mov_b32_e32 v30, v0
	v_mov_b32_e32 v31, v0
	v_mov_b32_e32 v40, v0
	v_mov_b32_e32 v41, v0
	v_mov_b32_e32 v42, v0
	v_mov_b32_e32 v43, v0
	v_mov_b32_e32 v44, v0
	v_mov_b32_e32 v45, v0
	v_mov_b32_e32 v46, v0
	v_mov_b32_e32 v47, v0
	v_mov_b32_e32 v56, v0
	v_mov_b32_e32 v57, v0
	v_mov_b32_e32 v58, v0
	v_mov_b32_e32 v59, v0
	v_mov_b32_e32 v60, v0
	v_mov_b32_e32 v61, v0
	v_mov_b32_e32 v62, v0
	v_mov_b32_e32 v63, v0
	v_mov_b32_e32 v64, v0
	v_mov_b32_e32 v65, v0
	v_mov_b32_e32 v66, v0
	v_mov_b32_e32 v67, v0
	v_mov_b32_e32 v68, v0
	v_mov_b32_e32 v69, v0
	v_mov_b32_e32 v70, v0
	v_mov_b32_e32 v71, v0
	v_mov_b32_e32 v80, v0
	v_mov_b32_e32 v81, v0
	v_mov_b32_e32 v82, v0
	v_mov_b32_e32 v83, v0
	v_mov_b32_e32 v84, v0
	v_mov_b32_e32 v85, v0
	v_mov_b32_e32 v86, v0
	v_mov_b32_e32 v87, v0
	v_mov_b32_e32 v96, v0
	v_mov_b32_e32 v97, v0
	v_mov_b32_e32 v98, v0
	v_mov_b32_e32 v99, v0
	v_mov_b32_e32 v100, v0
	v_mov_b32_e32 v101, v0
	v_mov_b32_e32 v102, v0
	v_mov_b32_e32 v103, v0
	v_mov_b32_e32 v104, v0
	v_mov_b32_e32 v105, v0
	v_mov_b32_e32 v106, v0
	v_mov_b32_e32 v107, v0
	v_mov_b32_e32 v108, v0
	v_mov_b32_e32 v109, v0
	v_mov_b32_e32 v110, v0
	v_mov_b32_e32 v111, v0
	v_mov_b32_e32 v72, v0
	v_mov_b32_e32 v73, v0
	v_mov_b32_e32 v74, v0
	v_mov_b32_e32 v75, v0
	v_mov_b32_e32 v76, v0
	v_mov_b32_e32 v77, v0
	v_mov_b32_e32 v78, v0
	v_mov_b32_e32 v79, v0
	v_mov_b32_e32 v88, v0
	v_mov_b32_e32 v89, v0
	v_mov_b32_e32 v90, v0
	v_mov_b32_e32 v91, v0
	v_mov_b32_e32 v92, v0
	v_mov_b32_e32 v93, v0
	v_mov_b32_e32 v94, v0
	v_mov_b32_e32 v95, v0
	v_mov_b32_e32 v112, v0
	v_mov_b32_e32 v113, v0
	v_mov_b32_e32 v114, v0
	v_mov_b32_e32 v115, v0
	v_mov_b32_e32 v116, v0
	v_mov_b32_e32 v117, v0
	v_mov_b32_e32 v118, v0
	v_mov_b32_e32 v119, v0
	v_mov_b32_e32 v120, v0
	v_mov_b32_e32 v121, v0
	v_mov_b32_e32 v122, v0
	v_mov_b32_e32 v123, v0
	v_mov_b32_e32 v124, v0
	v_mov_b32_e32 v125, v0
	v_mov_b32_e32 v126, v0
	v_mov_b32_e32 v127, v0
	s_waitcnt vmcnt(0)
	v_add_u32_e32 v148, 0x18000, v153
	v_add_u32_e32 v149, 0x1c000, v153
.LBB0_836:
	ds_read_b128 v[144:147], v157
	ds_read_b128 v[162:165], v157 offset:1024
	ds_read_b128 v[166:169], v157 offset:2048
	ds_read_b128 v[170:173], v157 offset:3072
	ds_read_b128 v[174:177], v159
	ds_read_b128 v[178:181], v159 offset:1024
	ds_read_b128 v[182:185], v159 offset:2048
	ds_read_b128 v[186:189], v159 offset:3072
	s_add_u32 s40, s38, 0xfff80080
	s_addc_u32 s41, s39, -1
	s_cmp_eq_u32 s59, 28
	s_cselect_b32 s43, s17, s41
	s_cselect_b32 s42, s51, s40
	s_cselect_b32 s41, s15, s58
	s_cselect_b32 s40, s56, s57
	s_add_i32 m0, s5, 0xc000
	ds_read_b128 v[190:193], v160
	ds_read_b128 v[194:197], v160 offset:1024
	ds_read_b128 v[198:201], v160 offset:2048
	ds_read_b128 v[202:205], v160 offset:3072
	ds_read_b128 v[206:209], v160 offset:4096
	ds_read_b128 v[210:213], v160 offset:5120
	ds_read_b128 v[214:217], v160 offset:6144
	ds_read_b128 v[218:221], v160 offset:7168
	global_load_lds_dwordx4 v136, s[38:39]
	s_add_i32 m0, s5, 0xe000
	s_nop 0
	global_load_lds_dwordx4 v138, s[38:39]
	s_waitcnt vmcnt(8)
	s_waitcnt lgkmcnt(0)
	s_barrier
	s_setprio 3
	s_waitcnt lgkmcnt(0)
	v_mfma_f32_16x16x32_bf16 v[124:127], v[144:147], v[190:193], v[124:127]
	v_mfma_f32_16x16x32_bf16 v[120:123], v[166:169], v[190:193], v[120:123]
	v_mfma_f32_16x16x32_bf16 v[116:119], v[144:147], v[198:201], v[116:119]
	v_mfma_f32_16x16x32_bf16 v[112:115], v[166:169], v[198:201], v[112:115]
	v_mfma_f32_16x16x32_bf16 v[92:95], v[144:147], v[206:209], v[92:95]
	v_mfma_f32_16x16x32_bf16 v[88:91], v[166:169], v[206:209], v[88:91]
	v_mfma_f32_16x16x32_bf16 v[76:79], v[144:147], v[214:217], v[76:79]
	v_mfma_f32_16x16x32_bf16 v[72:75], v[166:169], v[214:217], v[72:75]
	v_mfma_f32_16x16x32_bf16 v[124:127], v[162:165], v[194:197], v[124:127]
	v_mfma_f32_16x16x32_bf16 v[120:123], v[170:173], v[194:197], v[120:123]
	v_mfma_f32_16x16x32_bf16 v[116:119], v[162:165], v[202:205], v[116:119]
	v_mfma_f32_16x16x32_bf16 v[112:115], v[170:173], v[202:205], v[112:115]
	v_mfma_f32_16x16x32_bf16 v[92:95], v[162:165], v[210:213], v[92:95]
	v_mfma_f32_16x16x32_bf16 v[88:91], v[170:173], v[210:213], v[88:91]
	v_mfma_f32_16x16x32_bf16 v[76:79], v[162:165], v[218:221], v[76:79]
	v_mfma_f32_16x16x32_bf16 v[72:75], v[170:173], v[218:221], v[72:75]
	s_setprio 0
	s_setprio 3
	v_mfma_f32_16x16x32_bf16 v[108:111], v[174:177], v[190:193], v[108:111]
	v_mfma_f32_16x16x32_bf16 v[104:107], v[182:185], v[190:193], v[104:107]
	v_mfma_f32_16x16x32_bf16 v[100:103], v[174:177], v[198:201], v[100:103]
	v_mfma_f32_16x16x32_bf16 v[96:99], v[182:185], v[198:201], v[96:99]
	v_mfma_f32_16x16x32_bf16 v[84:87], v[174:177], v[206:209], v[84:87]
	v_mfma_f32_16x16x32_bf16 v[80:83], v[182:185], v[206:209], v[80:83]
	v_mfma_f32_16x16x32_bf16 v[68:71], v[174:177], v[214:217], v[68:71]
	v_mfma_f32_16x16x32_bf16 v[64:67], v[182:185], v[214:217], v[64:67]
	v_mfma_f32_16x16x32_bf16 v[108:111], v[178:181], v[194:197], v[108:111]
	v_mfma_f32_16x16x32_bf16 v[104:107], v[186:189], v[194:197], v[104:107]
	v_mfma_f32_16x16x32_bf16 v[100:103], v[178:181], v[202:205], v[100:103]
	v_mfma_f32_16x16x32_bf16 v[96:99], v[186:189], v[202:205], v[96:99]
	v_mfma_f32_16x16x32_bf16 v[84:87], v[178:181], v[210:213], v[84:87]
	v_mfma_f32_16x16x32_bf16 v[80:83], v[186:189], v[210:213], v[80:83]
	v_mfma_f32_16x16x32_bf16 v[68:71], v[178:181], v[218:221], v[68:71]
	v_mfma_f32_16x16x32_bf16 v[64:67], v[186:189], v[218:221], v[64:67]
	s_setprio 0
	s_barrier
	s_add_u32 s98, s40, s10
	s_addc_u32 s99, s41, s11
	s_add_u32 s100, s42, s10
	s_addc_u32 s101, s43, s11
	s_add_i32 s60, s47, s89
	s_mov_b32 m0, s60
	ds_read_b128 v[190:193], v160 offset:16384
	ds_read_b128 v[194:197], v160 offset:17408
	ds_read_b128 v[198:201], v160 offset:18432
	ds_read_b128 v[202:205], v160 offset:19456
	ds_read_b128 v[206:209], v160 offset:20480
	ds_read_b128 v[210:213], v160 offset:21504
	ds_read_b128 v[214:217], v160 offset:22528
	ds_read_b128 v[218:221], v160 offset:23552
	global_load_lds_dwordx4 v128, s[40:41]
	s_add_i32 m0, s60, 0x2000
	s_add_u32 s60, s40, 0x80000
	s_addc_u32 s61, s41, 0
	s_add_i32 s62, s48, s89
	global_load_lds_dwordx4 v130, s[40:41]
	s_mov_b32 m0, s62
	s_nop 0
	global_load_lds_dwordx4 v128, s[60:61]
	s_add_i32 m0, s62, 0x2000
	s_nop 0
	global_load_lds_dwordx4 v130, s[60:61]
	s_mov_b32 m0, s5
	s_nop 0
	global_load_lds_dwordx4 v134, s[42:43]
	s_mov_b32 m0, s28
	s_nop 0
	global_load_lds_dwordx4 v132, s[42:43]
	s_waitcnt vmcnt(8)
	s_waitcnt lgkmcnt(0)
	s_barrier
	s_setprio 3
	s_waitcnt lgkmcnt(0)
	v_mfma_f32_16x16x32_bf16 v[60:63], v[144:147], v[190:193], v[60:63]
	v_mfma_f32_16x16x32_bf16 v[56:59], v[166:169], v[190:193], v[56:59]
	v_mfma_f32_16x16x32_bf16 v[44:47], v[144:147], v[198:201], v[44:47]
	v_mfma_f32_16x16x32_bf16 v[40:43], v[166:169], v[198:201], v[40:43]
	v_mfma_f32_16x16x32_bf16 v[28:31], v[144:147], v[206:209], v[28:31]
	v_mfma_f32_16x16x32_bf16 v[24:27], v[166:169], v[206:209], v[24:27]
	v_mfma_f32_16x16x32_bf16 v[12:15], v[144:147], v[214:217], v[12:15]
	v_mfma_f32_16x16x32_bf16 v[8:11], v[166:169], v[214:217], v[8:11]
	v_mfma_f32_16x16x32_bf16 v[60:63], v[162:165], v[194:197], v[60:63]
	v_mfma_f32_16x16x32_bf16 v[56:59], v[170:173], v[194:197], v[56:59]
	v_mfma_f32_16x16x32_bf16 v[44:47], v[162:165], v[202:205], v[44:47]
	v_mfma_f32_16x16x32_bf16 v[40:43], v[170:173], v[202:205], v[40:43]
	v_mfma_f32_16x16x32_bf16 v[28:31], v[162:165], v[210:213], v[28:31]
	v_mfma_f32_16x16x32_bf16 v[24:27], v[170:173], v[210:213], v[24:27]
	v_mfma_f32_16x16x32_bf16 v[12:15], v[162:165], v[218:221], v[12:15]
	v_mfma_f32_16x16x32_bf16 v[8:11], v[170:173], v[218:221], v[8:11]
	s_setprio 0
	s_setprio 3
	v_mfma_f32_16x16x32_bf16 v[52:55], v[174:177], v[190:193], v[52:55]
	v_mfma_f32_16x16x32_bf16 v[48:51], v[182:185], v[190:193], v[48:51]
	v_mfma_f32_16x16x32_bf16 v[36:39], v[174:177], v[198:201], v[36:39]
	v_mfma_f32_16x16x32_bf16 v[32:35], v[182:185], v[198:201], v[32:35]
	v_mfma_f32_16x16x32_bf16 v[20:23], v[174:177], v[206:209], v[20:23]
	v_mfma_f32_16x16x32_bf16 v[16:19], v[182:185], v[206:209], v[16:19]
	v_mfma_f32_16x16x32_bf16 v[4:7], v[174:177], v[214:217], v[4:7]
	v_mfma_f32_16x16x32_bf16 v[0:3], v[182:185], v[214:217], v[0:3]
	v_mfma_f32_16x16x32_bf16 v[52:55], v[178:181], v[194:197], v[52:55]
	v_mfma_f32_16x16x32_bf16 v[48:51], v[186:189], v[194:197], v[48:51]
	v_mfma_f32_16x16x32_bf16 v[36:39], v[178:181], v[202:205], v[36:39]
	v_mfma_f32_16x16x32_bf16 v[32:35], v[186:189], v[202:205], v[32:35]
	v_mfma_f32_16x16x32_bf16 v[20:23], v[178:181], v[210:213], v[20:23]
	v_mfma_f32_16x16x32_bf16 v[16:19], v[186:189], v[210:213], v[16:19]
	v_mfma_f32_16x16x32_bf16 v[4:7], v[178:181], v[218:221], v[4:7]
	v_mfma_f32_16x16x32_bf16 v[0:3], v[186:189], v[218:221], v[0:3]
	s_setprio 0
	s_barrier
	s_add_i32 s60, 0, 0x18000
	s_add_i32 s61, 0, 0x1c000
	ds_read_b128 v[144:147], v148
	ds_read_b128 v[162:165], v148 offset:1024
	ds_read_b128 v[166:169], v148 offset:2048
	ds_read_b128 v[170:173], v148 offset:3072
	ds_read_b128 v[174:177], v149
	ds_read_b128 v[178:181], v149 offset:1024
	ds_read_b128 v[182:185], v149 offset:2048
	ds_read_b128 v[186:189], v149 offset:3072
	s_add_u32 s42, s42, 0x80000
	s_addc_u32 s43, s43, 0
	s_mov_b32 m0, s29
	ds_read_b128 v[190:193], v160 offset:32768
	ds_read_b128 v[194:197], v160 offset:33792
	ds_read_b128 v[198:201], v160 offset:34816
	ds_read_b128 v[202:205], v160 offset:35840
	ds_read_b128 v[206:209], v160 offset:36864
	ds_read_b128 v[210:213], v160 offset:37888
	ds_read_b128 v[214:217], v160 offset:38912
	ds_read_b128 v[218:221], v160 offset:39936
	global_load_lds_dwordx4 v134, s[42:43]
	s_mov_b32 m0, s37
	s_nop 0
	global_load_lds_dwordx4 v132, s[42:43]
	s_waitcnt vmcnt(8)
	s_waitcnt lgkmcnt(0)
	s_barrier
	s_setprio 3
	s_waitcnt lgkmcnt(0)
	v_mfma_f32_16x16x32_bf16 v[124:127], v[144:147], v[190:193], v[124:127]
	v_mfma_f32_16x16x32_bf16 v[120:123], v[166:169], v[190:193], v[120:123]
	v_mfma_f32_16x16x32_bf16 v[116:119], v[144:147], v[198:201], v[116:119]
	v_mfma_f32_16x16x32_bf16 v[112:115], v[166:169], v[198:201], v[112:115]
	v_mfma_f32_16x16x32_bf16 v[92:95], v[144:147], v[206:209], v[92:95]
	v_mfma_f32_16x16x32_bf16 v[88:91], v[166:169], v[206:209], v[88:91]
	v_mfma_f32_16x16x32_bf16 v[76:79], v[144:147], v[214:217], v[76:79]
	v_mfma_f32_16x16x32_bf16 v[72:75], v[166:169], v[214:217], v[72:75]
	v_mfma_f32_16x16x32_bf16 v[124:127], v[162:165], v[194:197], v[124:127]
	v_mfma_f32_16x16x32_bf16 v[120:123], v[170:173], v[194:197], v[120:123]
	v_mfma_f32_16x16x32_bf16 v[116:119], v[162:165], v[202:205], v[116:119]
	v_mfma_f32_16x16x32_bf16 v[112:115], v[170:173], v[202:205], v[112:115]
	v_mfma_f32_16x16x32_bf16 v[92:95], v[162:165], v[210:213], v[92:95]
	v_mfma_f32_16x16x32_bf16 v[88:91], v[170:173], v[210:213], v[88:91]
	v_mfma_f32_16x16x32_bf16 v[76:79], v[162:165], v[218:221], v[76:79]
	v_mfma_f32_16x16x32_bf16 v[72:75], v[170:173], v[218:221], v[72:75]
	s_setprio 0
	s_setprio 3
	v_mfma_f32_16x16x32_bf16 v[108:111], v[174:177], v[190:193], v[108:111]
	v_mfma_f32_16x16x32_bf16 v[104:107], v[182:185], v[190:193], v[104:107]
	v_mfma_f32_16x16x32_bf16 v[100:103], v[174:177], v[198:201], v[100:103]
	v_mfma_f32_16x16x32_bf16 v[96:99], v[182:185], v[198:201], v[96:99]
	v_mfma_f32_16x16x32_bf16 v[84:87], v[174:177], v[206:209], v[84:87]
	v_mfma_f32_16x16x32_bf16 v[80:83], v[182:185], v[206:209], v[80:83]
	v_mfma_f32_16x16x32_bf16 v[68:71], v[174:177], v[214:217], v[68:71]
	v_mfma_f32_16x16x32_bf16 v[64:67], v[182:185], v[214:217], v[64:67]
	v_mfma_f32_16x16x32_bf16 v[108:111], v[178:181], v[194:197], v[108:111]
	v_mfma_f32_16x16x32_bf16 v[104:107], v[186:189], v[194:197], v[104:107]
	v_mfma_f32_16x16x32_bf16 v[100:103], v[178:181], v[202:205], v[100:103]
	v_mfma_f32_16x16x32_bf16 v[96:99], v[186:189], v[202:205], v[96:99]
	v_mfma_f32_16x16x32_bf16 v[84:87], v[178:181], v[210:213], v[84:87]
	v_mfma_f32_16x16x32_bf16 v[80:83], v[186:189], v[210:213], v[80:83]
	v_mfma_f32_16x16x32_bf16 v[68:71], v[178:181], v[218:221], v[68:71]
	v_mfma_f32_16x16x32_bf16 v[64:67], v[186:189], v[218:221], v[64:67]
	s_setprio 0
	s_barrier
	s_add_i32 s42, s60, s89
	s_mov_b32 m0, s42
	ds_read_b128 v[190:193], v160 offset:49152
	ds_read_b128 v[194:197], v160 offset:50176
	ds_read_b128 v[198:201], v160 offset:51200
	ds_read_b128 v[202:205], v160 offset:52224
	ds_read_b128 v[206:209], v160 offset:53248
	ds_read_b128 v[210:213], v160 offset:54272
	ds_read_b128 v[214:217], v160 offset:55296
	ds_read_b128 v[218:221], v160 offset:56320
	global_load_lds_dwordx4 v128, s[98:99]
	s_add_i32 m0, s42, 0x2000
	s_add_u32 s40, s40, 0x80080
	s_addc_u32 s41, s41, 0
	s_add_i32 s42, s61, s89
	global_load_lds_dwordx4 v130, s[98:99]
	s_mov_b32 m0, s42
	s_nop 0
	global_load_lds_dwordx4 v128, s[40:41]
	s_add_i32 m0, s42, 0x2000
	s_nop 0
	global_load_lds_dwordx4 v130, s[40:41]
	s_mov_b32 m0, s45
	s_nop 0
	global_load_lds_dwordx4 v134, s[100:101]
	s_mov_b32 m0, s46
	s_nop 0
	global_load_lds_dwordx4 v132, s[100:101]
	s_waitcnt vmcnt(8)
	s_waitcnt lgkmcnt(0)
	s_barrier
	s_setprio 3
	s_waitcnt lgkmcnt(0)
	v_mfma_f32_16x16x32_bf16 v[60:63], v[144:147], v[190:193], v[60:63]
	v_mfma_f32_16x16x32_bf16 v[56:59], v[166:169], v[190:193], v[56:59]
	v_mfma_f32_16x16x32_bf16 v[44:47], v[144:147], v[198:201], v[44:47]
	v_mfma_f32_16x16x32_bf16 v[40:43], v[166:169], v[198:201], v[40:43]
	v_mfma_f32_16x16x32_bf16 v[28:31], v[144:147], v[206:209], v[28:31]
	v_mfma_f32_16x16x32_bf16 v[24:27], v[166:169], v[206:209], v[24:27]
	v_mfma_f32_16x16x32_bf16 v[12:15], v[144:147], v[214:217], v[12:15]
	v_mfma_f32_16x16x32_bf16 v[8:11], v[166:169], v[214:217], v[8:11]
	v_mfma_f32_16x16x32_bf16 v[60:63], v[162:165], v[194:197], v[60:63]
	v_mfma_f32_16x16x32_bf16 v[56:59], v[170:173], v[194:197], v[56:59]
	v_mfma_f32_16x16x32_bf16 v[44:47], v[162:165], v[202:205], v[44:47]
	v_mfma_f32_16x16x32_bf16 v[40:43], v[170:173], v[202:205], v[40:43]
	v_mfma_f32_16x16x32_bf16 v[28:31], v[162:165], v[210:213], v[28:31]
	v_mfma_f32_16x16x32_bf16 v[24:27], v[170:173], v[210:213], v[24:27]
	v_mfma_f32_16x16x32_bf16 v[12:15], v[162:165], v[218:221], v[12:15]
	v_mfma_f32_16x16x32_bf16 v[8:11], v[170:173], v[218:221], v[8:11]
	s_setprio 0
	s_setprio 3
	v_mfma_f32_16x16x32_bf16 v[52:55], v[174:177], v[190:193], v[52:55]
	v_mfma_f32_16x16x32_bf16 v[48:51], v[182:185], v[190:193], v[48:51]
	v_mfma_f32_16x16x32_bf16 v[36:39], v[174:177], v[198:201], v[36:39]
	v_mfma_f32_16x16x32_bf16 v[32:35], v[182:185], v[198:201], v[32:35]
	v_mfma_f32_16x16x32_bf16 v[20:23], v[174:177], v[206:209], v[20:23]
	v_mfma_f32_16x16x32_bf16 v[16:19], v[182:185], v[206:209], v[16:19]
	v_mfma_f32_16x16x32_bf16 v[4:7], v[174:177], v[214:217], v[4:7]
	v_mfma_f32_16x16x32_bf16 v[0:3], v[182:185], v[214:217], v[0:3]
	v_mfma_f32_16x16x32_bf16 v[52:55], v[178:181], v[194:197], v[52:55]
	v_mfma_f32_16x16x32_bf16 v[48:51], v[186:189], v[194:197], v[48:51]
	v_mfma_f32_16x16x32_bf16 v[36:39], v[178:181], v[202:205], v[36:39]
	v_mfma_f32_16x16x32_bf16 v[32:35], v[186:189], v[202:205], v[32:35]
	v_mfma_f32_16x16x32_bf16 v[20:23], v[178:181], v[210:213], v[20:23]
	v_mfma_f32_16x16x32_bf16 v[16:19], v[186:189], v[210:213], v[16:19]
	v_mfma_f32_16x16x32_bf16 v[4:7], v[178:181], v[218:221], v[4:7]
	v_mfma_f32_16x16x32_bf16 v[0:3], v[186:189], v[218:221], v[0:3]
	s_setprio 0
	s_barrier
	s_add_i32 s59, s59, 2
	s_add_u32 s38, s38, 0x100
	s_addc_u32 s39, s39, 0
	s_add_u32 s57, s57, 0x100
	s_addc_u32 s58, s58, 0
	s_cmp_gt_u32 s59, 29
	s_cbranch_scc0 .LBB0_836
	s_and_b64 vcc, exec, s[64:65]
	s_cbranch_vccz .LBB0_839
	s_barrier

.LBB0_925:
	s_add_u32 s41, s16, 0x100
	v_mov_b32_e32 v0, 0
	s_addc_u32 s42, s17, 0
	s_mov_b32 s43, -2
	v_mov_b32_e32 v1, v0
	v_mov_b32_e32 v2, v0
	v_mov_b32_e32 v3, v0
	v_mov_b32_e32 v4, v0
	v_mov_b32_e32 v5, v0
	v_mov_b32_e32 v6, v0
	v_mov_b32_e32 v7, v0
	v_mov_b32_e32 v12, v0
	v_mov_b32_e32 v13, v0
	v_mov_b32_e32 v14, v0
	v_mov_b32_e32 v15, v0
	v_mov_b32_e32 v20, v0
	v_mov_b32_e32 v21, v0
	v_mov_b32_e32 v22, v0
	v_mov_b32_e32 v23, v0
	v_mov_b32_e32 v28, v0
	v_mov_b32_e32 v29, v0
	v_mov_b32_e32 v30, v0
	v_mov_b32_e32 v31, v0
	v_mov_b32_e32 v36, v0
	v_mov_b32_e32 v37, v0
	v_mov_b32_e32 v38, v0
	v_mov_b32_e32 v39, v0
	v_mov_b32_e32 v44, v0
	v_mov_b32_e32 v45, v0
	v_mov_b32_e32 v46, v0
	v_mov_b32_e32 v47, v0
	v_mov_b32_e32 v52, v0
	v_mov_b32_e32 v53, v0
	v_mov_b32_e32 v54, v0
	v_mov_b32_e32 v55, v0
	v_mov_b32_e32 v8, v0
	v_mov_b32_e32 v9, v0
	v_mov_b32_e32 v10, v0
	v_mov_b32_e32 v11, v0
	v_mov_b32_e32 v16, v0
	v_mov_b32_e32 v17, v0
	v_mov_b32_e32 v18, v0
	v_mov_b32_e32 v19, v0
	v_mov_b32_e32 v24, v0
	v_mov_b32_e32 v25, v0
	v_mov_b32_e32 v26, v0
	v_mov_b32_e32 v27, v0
	v_mov_b32_e32 v32, v0
	v_mov_b32_e32 v33, v0
	v_mov_b32_e32 v34, v0
	v_mov_b32_e32 v35, v0
	v_mov_b32_e32 v40, v0
	v_mov_b32_e32 v41, v0
	v_mov_b32_e32 v42, v0
	v_mov_b32_e32 v43, v0
	v_mov_b32_e32 v48, v0
	v_mov_b32_e32 v49, v0
	v_mov_b32_e32 v50, v0
	v_mov_b32_e32 v51, v0
	v_mov_b32_e32 v56, v0
	v_mov_b32_e32 v57, v0
	v_mov_b32_e32 v58, v0
	v_mov_b32_e32 v59, v0
	v_mov_b32_e32 v60, v0
	v_mov_b32_e32 v61, v0
	v_mov_b32_e32 v62, v0
	v_mov_b32_e32 v63, v0
	v_mov_b32_e32 v64, v0
	v_mov_b32_e32 v65, v0
	v_mov_b32_e32 v66, v0
	v_mov_b32_e32 v67, v0
	v_mov_b32_e32 v68, v0
	v_mov_b32_e32 v69, v0
	v_mov_b32_e32 v70, v0
	v_mov_b32_e32 v71, v0
	v_mov_b32_e32 v76, v0
	v_mov_b32_e32 v77, v0
	v_mov_b32_e32 v78, v0
	v_mov_b32_e32 v79, v0
	v_mov_b32_e32 v84, v0
	v_mov_b32_e32 v85, v0
	v_mov_b32_e32 v86, v0
	v_mov_b32_e32 v87, v0
	v_mov_b32_e32 v92, v0
	v_mov_b32_e32 v93, v0
	v_mov_b32_e32 v94, v0
	v_mov_b32_e32 v95, v0
	v_mov_b32_e32 v100, v0
	v_mov_b32_e32 v101, v0
	v_mov_b32_e32 v102, v0
	v_mov_b32_e32 v103, v0
	v_mov_b32_e32 v108, v0
	v_mov_b32_e32 v109, v0
	v_mov_b32_e32 v110, v0
	v_mov_b32_e32 v111, v0
	v_mov_b32_e32 v116, v0
	v_mov_b32_e32 v117, v0
	v_mov_b32_e32 v118, v0
	v_mov_b32_e32 v119, v0
	v_mov_b32_e32 v72, v0
	v_mov_b32_e32 v73, v0
	v_mov_b32_e32 v74, v0
	v_mov_b32_e32 v75, v0
	v_mov_b32_e32 v80, v0
	v_mov_b32_e32 v81, v0
	v_mov_b32_e32 v82, v0
	v_mov_b32_e32 v83, v0
	v_mov_b32_e32 v88, v0
	v_mov_b32_e32 v89, v0
	v_mov_b32_e32 v90, v0
	v_mov_b32_e32 v91, v0
	v_mov_b32_e32 v96, v0
	v_mov_b32_e32 v97, v0
	v_mov_b32_e32 v98, v0
	v_mov_b32_e32 v99, v0
	v_mov_b32_e32 v104, v0
	v_mov_b32_e32 v105, v0
	v_mov_b32_e32 v106, v0
	v_mov_b32_e32 v107, v0
	v_mov_b32_e32 v112, v0
	v_mov_b32_e32 v113, v0
	v_mov_b32_e32 v114, v0
	v_mov_b32_e32 v115, v0
	v_mov_b32_e32 v120, v0
	v_mov_b32_e32 v121, v0
	v_mov_b32_e32 v122, v0
	v_mov_b32_e32 v123, v0
	v_mov_b32_e32 v124, v0
	v_mov_b32_e32 v125, v0
	v_mov_b32_e32 v126, v0
	v_mov_b32_e32 v127, v0
	s_waitcnt vmcnt(0)
	v_add_u32_e32 v210, 0x18000, v145
	v_add_u32_e32 v211, 0x1c000, v145
.LBB0_926:
	ds_read_b128 v[140:143], v147
	ds_read_b128 v[150:153], v147 offset:1024
	ds_read_b128 v[154:157], v147 offset:2048
	ds_read_b128 v[158:161], v147 offset:3072
	ds_read_b128 v[162:165], v148
	ds_read_b128 v[166:169], v148 offset:1024
	ds_read_b128 v[170:173], v148 offset:2048
	ds_read_b128 v[174:177], v148 offset:3072
	s_add_u32 s16, s14, 0x100
	s_addc_u32 s17, s15, 0
	s_cmpk_eq_i32 s43, 0x54
	s_cselect_b32 s21, s5, s17
	s_cselect_b32 s20, s4, s16
	s_cselect_b32 s19, s13, s42
	s_cselect_b32 s18, s12, s41
	s_add_i32 m0, s3, 0xc000
	ds_read_b128 v[178:181], v149
	ds_read_b128 v[182:185], v149 offset:1024
	ds_read_b128 v[186:189], v149 offset:2048
	ds_read_b128 v[190:193], v149 offset:3072
	ds_read_b128 v[194:197], v149 offset:4096
	ds_read_b128 v[198:201], v149 offset:5120
	ds_read_b128 v[202:205], v149 offset:6144
	ds_read_b128 v[206:209], v149 offset:7168
	global_load_lds_dwordx4 v132, s[14:15]
	s_add_i32 m0, s3, 0xe000
	s_nop 0
	global_load_lds_dwordx4 v134, s[14:15]
	s_waitcnt vmcnt(8)
	s_waitcnt lgkmcnt(0)
	s_barrier
	s_setprio 3
	s_waitcnt lgkmcnt(0)
	v_mfma_f32_16x16x32_bf16 v[124:127], v[140:143], v[178:181], v[124:127]
	v_mfma_f32_16x16x32_bf16 v[120:123], v[154:157], v[178:181], v[120:123]
	v_mfma_f32_16x16x32_bf16 v[112:115], v[140:143], v[186:189], v[112:115]
	v_mfma_f32_16x16x32_bf16 v[104:107], v[154:157], v[186:189], v[104:107]
	v_mfma_f32_16x16x32_bf16 v[96:99], v[140:143], v[194:197], v[96:99]
	v_mfma_f32_16x16x32_bf16 v[88:91], v[154:157], v[194:197], v[88:91]
	v_mfma_f32_16x16x32_bf16 v[80:83], v[140:143], v[202:205], v[80:83]
	v_mfma_f32_16x16x32_bf16 v[72:75], v[154:157], v[202:205], v[72:75]
	v_mfma_f32_16x16x32_bf16 v[124:127], v[150:153], v[182:185], v[124:127]
	v_mfma_f32_16x16x32_bf16 v[120:123], v[158:161], v[182:185], v[120:123]
	v_mfma_f32_16x16x32_bf16 v[112:115], v[150:153], v[190:193], v[112:115]
	v_mfma_f32_16x16x32_bf16 v[104:107], v[158:161], v[190:193], v[104:107]
	v_mfma_f32_16x16x32_bf16 v[96:99], v[150:153], v[198:201], v[96:99]
	v_mfma_f32_16x16x32_bf16 v[88:91], v[158:161], v[198:201], v[88:91]
	v_mfma_f32_16x16x32_bf16 v[80:83], v[150:153], v[206:209], v[80:83]
	v_mfma_f32_16x16x32_bf16 v[72:75], v[158:161], v[206:209], v[72:75]
	s_setprio 0
	s_setprio 3
	v_mfma_f32_16x16x32_bf16 v[116:119], v[162:165], v[178:181], v[116:119]
	v_mfma_f32_16x16x32_bf16 v[108:111], v[170:173], v[178:181], v[108:111]
	v_mfma_f32_16x16x32_bf16 v[100:103], v[162:165], v[186:189], v[100:103]
	v_mfma_f32_16x16x32_bf16 v[92:95], v[170:173], v[186:189], v[92:95]
	v_mfma_f32_16x16x32_bf16 v[84:87], v[162:165], v[194:197], v[84:87]
	v_mfma_f32_16x16x32_bf16 v[76:79], v[170:173], v[194:197], v[76:79]
	v_mfma_f32_16x16x32_bf16 v[68:71], v[162:165], v[202:205], v[68:71]
	v_mfma_f32_16x16x32_bf16 v[64:67], v[170:173], v[202:205], v[64:67]
	v_mfma_f32_16x16x32_bf16 v[116:119], v[166:169], v[182:185], v[116:119]
	v_mfma_f32_16x16x32_bf16 v[108:111], v[174:177], v[182:185], v[108:111]
	v_mfma_f32_16x16x32_bf16 v[100:103], v[166:169], v[190:193], v[100:103]
	v_mfma_f32_16x16x32_bf16 v[92:95], v[174:177], v[190:193], v[92:95]
	v_mfma_f32_16x16x32_bf16 v[84:87], v[166:169], v[198:201], v[84:87]
	v_mfma_f32_16x16x32_bf16 v[76:79], v[174:177], v[198:201], v[76:79]
	v_mfma_f32_16x16x32_bf16 v[68:71], v[166:169], v[206:209], v[68:71]
	v_mfma_f32_16x16x32_bf16 v[64:67], v[174:177], v[206:209], v[64:67]
	s_setprio 0
	s_barrier
	s_add_u32 s98, s18, s10
	s_addc_u32 s99, s19, s11
	s_add_u32 s100, s20, s10
	s_addc_u32 s101, s21, s11
	s_add_i32 s14, s29, s89
	s_mov_b32 m0, s14
	ds_read_b128 v[178:181], v149 offset:16384
	ds_read_b128 v[182:185], v149 offset:17408
	ds_read_b128 v[186:189], v149 offset:18432
	ds_read_b128 v[190:193], v149 offset:19456
	ds_read_b128 v[194:197], v149 offset:20480
	ds_read_b128 v[198:201], v149 offset:21504
	ds_read_b128 v[202:205], v149 offset:22528
	ds_read_b128 v[206:209], v149 offset:23552
	global_load_lds_dwordx4 v128, s[18:19]
	s_add_i32 m0, s14, 0x2000
	s_add_u32 s14, s18, 0x160000
	s_addc_u32 s15, s19, 0
	s_add_i32 s44, s36, s89
	global_load_lds_dwordx4 v130, s[18:19]
	s_mov_b32 m0, s44
	s_nop 0
	global_load_lds_dwordx4 v128, s[14:15]
	s_add_i32 m0, s44, 0x2000
	s_nop 0
	global_load_lds_dwordx4 v130, s[14:15]
	s_mov_b32 m0, s3
	s_nop 0
	global_load_lds_dwordx4 v128, s[20:21]
	s_mov_b32 m0, s22
	s_nop 0
	global_load_lds_dwordx4 v130, s[20:21]
	s_waitcnt vmcnt(8)
	s_waitcnt lgkmcnt(0)
	s_barrier
	s_setprio 3
	s_waitcnt lgkmcnt(0)
	v_mfma_f32_16x16x32_bf16 v[60:63], v[140:143], v[178:181], v[60:63]
	v_mfma_f32_16x16x32_bf16 v[56:59], v[154:157], v[178:181], v[56:59]
	v_mfma_f32_16x16x32_bf16 v[48:51], v[140:143], v[186:189], v[48:51]
	v_mfma_f32_16x16x32_bf16 v[40:43], v[154:157], v[186:189], v[40:43]
	v_mfma_f32_16x16x32_bf16 v[32:35], v[140:143], v[194:197], v[32:35]
	v_mfma_f32_16x16x32_bf16 v[24:27], v[154:157], v[194:197], v[24:27]
	v_mfma_f32_16x16x32_bf16 v[16:19], v[140:143], v[202:205], v[16:19]
	v_mfma_f32_16x16x32_bf16 v[8:11], v[154:157], v[202:205], v[8:11]
	v_mfma_f32_16x16x32_bf16 v[60:63], v[150:153], v[182:185], v[60:63]
	v_mfma_f32_16x16x32_bf16 v[56:59], v[158:161], v[182:185], v[56:59]
	v_mfma_f32_16x16x32_bf16 v[48:51], v[150:153], v[190:193], v[48:51]
	v_mfma_f32_16x16x32_bf16 v[40:43], v[158:161], v[190:193], v[40:43]
	v_mfma_f32_16x16x32_bf16 v[32:35], v[150:153], v[198:201], v[32:35]
	v_mfma_f32_16x16x32_bf16 v[24:27], v[158:161], v[198:201], v[24:27]
	v_mfma_f32_16x16x32_bf16 v[16:19], v[150:153], v[206:209], v[16:19]
	v_mfma_f32_16x16x32_bf16 v[8:11], v[158:161], v[206:209], v[8:11]
	s_setprio 0
	s_setprio 3
	v_mfma_f32_16x16x32_bf16 v[52:55], v[162:165], v[178:181], v[52:55]
	v_mfma_f32_16x16x32_bf16 v[44:47], v[170:173], v[178:181], v[44:47]
	v_mfma_f32_16x16x32_bf16 v[36:39], v[162:165], v[186:189], v[36:39]
	v_mfma_f32_16x16x32_bf16 v[28:31], v[170:173], v[186:189], v[28:31]
	v_mfma_f32_16x16x32_bf16 v[20:23], v[162:165], v[194:197], v[20:23]
	v_mfma_f32_16x16x32_bf16 v[12:15], v[170:173], v[194:197], v[12:15]
	v_mfma_f32_16x16x32_bf16 v[4:7], v[162:165], v[202:205], v[4:7]
	v_mfma_f32_16x16x32_bf16 v[0:3], v[170:173], v[202:205], v[0:3]
	v_mfma_f32_16x16x32_bf16 v[52:55], v[166:169], v[182:185], v[52:55]
	v_mfma_f32_16x16x32_bf16 v[44:47], v[174:177], v[182:185], v[44:47]
	v_mfma_f32_16x16x32_bf16 v[36:39], v[166:169], v[190:193], v[36:39]
	v_mfma_f32_16x16x32_bf16 v[28:31], v[174:177], v[190:193], v[28:31]
	v_mfma_f32_16x16x32_bf16 v[20:23], v[166:169], v[198:201], v[20:23]
	v_mfma_f32_16x16x32_bf16 v[12:15], v[174:177], v[198:201], v[12:15]
	v_mfma_f32_16x16x32_bf16 v[4:7], v[166:169], v[206:209], v[4:7]
	v_mfma_f32_16x16x32_bf16 v[0:3], v[174:177], v[206:209], v[0:3]
	s_setprio 0
	s_barrier
	s_add_i32 s44, 0, 0x18000
	s_add_i32 s45, 0, 0x1c000
	ds_read_b128 v[140:143], v210
	ds_read_b128 v[150:153], v210 offset:1024
	ds_read_b128 v[154:157], v210 offset:2048
	ds_read_b128 v[158:161], v210 offset:3072
	ds_read_b128 v[162:165], v211
	ds_read_b128 v[166:169], v211 offset:1024
	ds_read_b128 v[170:173], v211 offset:2048
	ds_read_b128 v[174:177], v211 offset:3072
	s_add_u32 s14, s20, 0x160000
	s_addc_u32 s15, s21, 0
	s_mov_b32 m0, s23
	ds_read_b128 v[178:181], v149 offset:32768
	ds_read_b128 v[182:185], v149 offset:33792
	ds_read_b128 v[186:189], v149 offset:34816
	ds_read_b128 v[190:193], v149 offset:35840
	ds_read_b128 v[194:197], v149 offset:36864
	ds_read_b128 v[198:201], v149 offset:37888
	ds_read_b128 v[202:205], v149 offset:38912
	ds_read_b128 v[206:209], v149 offset:39936
	global_load_lds_dwordx4 v128, s[14:15]
	s_mov_b32 m0, s25
	s_nop 0
	global_load_lds_dwordx4 v130, s[14:15]
	s_waitcnt vmcnt(8)
	s_waitcnt lgkmcnt(0)
	s_barrier
	s_setprio 3
	s_waitcnt lgkmcnt(0)
	v_mfma_f32_16x16x32_bf16 v[124:127], v[140:143], v[178:181], v[124:127]
	v_mfma_f32_16x16x32_bf16 v[120:123], v[154:157], v[178:181], v[120:123]
	v_mfma_f32_16x16x32_bf16 v[112:115], v[140:143], v[186:189], v[112:115]
	v_mfma_f32_16x16x32_bf16 v[104:107], v[154:157], v[186:189], v[104:107]
	v_mfma_f32_16x16x32_bf16 v[96:99], v[140:143], v[194:197], v[96:99]
	v_mfma_f32_16x16x32_bf16 v[88:91], v[154:157], v[194:197], v[88:91]
	v_mfma_f32_16x16x32_bf16 v[80:83], v[140:143], v[202:205], v[80:83]
	v_mfma_f32_16x16x32_bf16 v[72:75], v[154:157], v[202:205], v[72:75]
	v_mfma_f32_16x16x32_bf16 v[124:127], v[150:153], v[182:185], v[124:127]
	v_mfma_f32_16x16x32_bf16 v[120:123], v[158:161], v[182:185], v[120:123]
	v_mfma_f32_16x16x32_bf16 v[112:115], v[150:153], v[190:193], v[112:115]
	v_mfma_f32_16x16x32_bf16 v[104:107], v[158:161], v[190:193], v[104:107]
	v_mfma_f32_16x16x32_bf16 v[96:99], v[150:153], v[198:201], v[96:99]
	v_mfma_f32_16x16x32_bf16 v[88:91], v[158:161], v[198:201], v[88:91]
	v_mfma_f32_16x16x32_bf16 v[80:83], v[150:153], v[206:209], v[80:83]
	v_mfma_f32_16x16x32_bf16 v[72:75], v[158:161], v[206:209], v[72:75]
	s_setprio 0
	s_setprio 3
	v_mfma_f32_16x16x32_bf16 v[116:119], v[162:165], v[178:181], v[116:119]
	v_mfma_f32_16x16x32_bf16 v[108:111], v[170:173], v[178:181], v[108:111]
	v_mfma_f32_16x16x32_bf16 v[100:103], v[162:165], v[186:189], v[100:103]
	v_mfma_f32_16x16x32_bf16 v[92:95], v[170:173], v[186:189], v[92:95]
	v_mfma_f32_16x16x32_bf16 v[84:87], v[162:165], v[194:197], v[84:87]
	v_mfma_f32_16x16x32_bf16 v[76:79], v[170:173], v[194:197], v[76:79]
	v_mfma_f32_16x16x32_bf16 v[68:71], v[162:165], v[202:205], v[68:71]
	v_mfma_f32_16x16x32_bf16 v[64:67], v[170:173], v[202:205], v[64:67]
	v_mfma_f32_16x16x32_bf16 v[116:119], v[166:169], v[182:185], v[116:119]
	v_mfma_f32_16x16x32_bf16 v[108:111], v[174:177], v[182:185], v[108:111]
	v_mfma_f32_16x16x32_bf16 v[100:103], v[166:169], v[190:193], v[100:103]
	v_mfma_f32_16x16x32_bf16 v[92:95], v[174:177], v[190:193], v[92:95]
	v_mfma_f32_16x16x32_bf16 v[84:87], v[166:169], v[198:201], v[84:87]
	v_mfma_f32_16x16x32_bf16 v[76:79], v[174:177], v[198:201], v[76:79]
	v_mfma_f32_16x16x32_bf16 v[68:71], v[166:169], v[206:209], v[68:71]
	v_mfma_f32_16x16x32_bf16 v[64:67], v[174:177], v[206:209], v[64:67]
	s_setprio 0
	s_barrier
	s_add_i32 s14, s44, s89
	s_mov_b32 m0, s14
	ds_read_b128 v[178:181], v149 offset:49152
	ds_read_b128 v[182:185], v149 offset:50176
	ds_read_b128 v[186:189], v149 offset:51200
	ds_read_b128 v[190:193], v149 offset:52224
	ds_read_b128 v[194:197], v149 offset:53248
	ds_read_b128 v[198:201], v149 offset:54272
	ds_read_b128 v[202:205], v149 offset:55296
	ds_read_b128 v[206:209], v149 offset:56320
	global_load_lds_dwordx4 v128, s[98:99]
	s_add_i32 m0, s14, 0x2000
	s_add_u32 s14, s18, 0x160080
	s_addc_u32 s15, s19, 0
	s_add_i32 s18, s45, s89
	global_load_lds_dwordx4 v130, s[98:99]
	s_mov_b32 m0, s18
	s_nop 0
	global_load_lds_dwordx4 v128, s[14:15]
	s_add_i32 m0, s18, 0x2000
	s_nop 0
	global_load_lds_dwordx4 v130, s[14:15]
	s_mov_b32 m0, s27
	s_nop 0
	global_load_lds_dwordx4 v128, s[100:101]
	s_mov_b32 m0, s28
	s_nop 0
	global_load_lds_dwordx4 v130, s[100:101]
	s_waitcnt vmcnt(8)
	s_waitcnt lgkmcnt(0)
	s_barrier
	s_setprio 3
	s_waitcnt lgkmcnt(0)
	v_mfma_f32_16x16x32_bf16 v[60:63], v[140:143], v[178:181], v[60:63]
	v_mfma_f32_16x16x32_bf16 v[56:59], v[154:157], v[178:181], v[56:59]
	v_mfma_f32_16x16x32_bf16 v[48:51], v[140:143], v[186:189], v[48:51]
	v_mfma_f32_16x16x32_bf16 v[40:43], v[154:157], v[186:189], v[40:43]
	v_mfma_f32_16x16x32_bf16 v[32:35], v[140:143], v[194:197], v[32:35]
	v_mfma_f32_16x16x32_bf16 v[24:27], v[154:157], v[194:197], v[24:27]
	v_mfma_f32_16x16x32_bf16 v[16:19], v[140:143], v[202:205], v[16:19]
	v_mfma_f32_16x16x32_bf16 v[8:11], v[154:157], v[202:205], v[8:11]
	v_mfma_f32_16x16x32_bf16 v[60:63], v[150:153], v[182:185], v[60:63]
	v_mfma_f32_16x16x32_bf16 v[56:59], v[158:161], v[182:185], v[56:59]
	v_mfma_f32_16x16x32_bf16 v[48:51], v[150:153], v[190:193], v[48:51]
	v_mfma_f32_16x16x32_bf16 v[40:43], v[158:161], v[190:193], v[40:43]
	v_mfma_f32_16x16x32_bf16 v[32:35], v[150:153], v[198:201], v[32:35]
	v_mfma_f32_16x16x32_bf16 v[24:27], v[158:161], v[198:201], v[24:27]
	v_mfma_f32_16x16x32_bf16 v[16:19], v[150:153], v[206:209], v[16:19]
	v_mfma_f32_16x16x32_bf16 v[8:11], v[158:161], v[206:209], v[8:11]
	s_setprio 0
	s_setprio 3
	v_mfma_f32_16x16x32_bf16 v[52:55], v[162:165], v[178:181], v[52:55]
	v_mfma_f32_16x16x32_bf16 v[44:47], v[170:173], v[178:181], v[44:47]
	v_mfma_f32_16x16x32_bf16 v[36:39], v[162:165], v[186:189], v[36:39]
	v_mfma_f32_16x16x32_bf16 v[28:31], v[170:173], v[186:189], v[28:31]
	v_mfma_f32_16x16x32_bf16 v[20:23], v[162:165], v[194:197], v[20:23]
	v_mfma_f32_16x16x32_bf16 v[12:15], v[170:173], v[194:197], v[12:15]
	v_mfma_f32_16x16x32_bf16 v[4:7], v[162:165], v[202:205], v[4:7]
	v_mfma_f32_16x16x32_bf16 v[0:3], v[170:173], v[202:205], v[0:3]
	v_mfma_f32_16x16x32_bf16 v[52:55], v[166:169], v[182:185], v[52:55]
	v_mfma_f32_16x16x32_bf16 v[44:47], v[174:177], v[182:185], v[44:47]
	v_mfma_f32_16x16x32_bf16 v[36:39], v[166:169], v[190:193], v[36:39]
	v_mfma_f32_16x16x32_bf16 v[28:31], v[174:177], v[190:193], v[28:31]
	v_mfma_f32_16x16x32_bf16 v[20:23], v[166:169], v[198:201], v[20:23]
	v_mfma_f32_16x16x32_bf16 v[12:15], v[174:177], v[198:201], v[12:15]
	v_mfma_f32_16x16x32_bf16 v[4:7], v[166:169], v[206:209], v[4:7]
	v_mfma_f32_16x16x32_bf16 v[0:3], v[174:177], v[206:209], v[0:3]
	s_setprio 0
	s_barrier
	s_add_i32 s43, s43, 2
	s_add_u32 s41, s41, 0x100
	s_addc_u32 s42, s42, 0
	s_cmpk_gt_u32 s43, 0x55
	s_mov_b64 s[14:15], s[16:17]
	s_cbranch_scc0 .LBB0_926
	s_and_b64 vcc, exec, s[64:65]
	s_cbranch_vccz .LBB0_929
	s_barrier
